# gate/up GEMM k-loop and SwiGLU epilogue rewritten for v_mfma_f32_16x16x32_bf16 (same bf16 operands, f32 accumulate)
# speedup vs baseline: 1.1082x; 1.0355x over previous
.LBB0_82:
	s_nop 2
	v_and_b32_e32 v99, 15, v129
	v_lshl_or_b32 v96, s20, 6, v99
	v_lshl_add_u32 v96, v151, 5, v96
	v_bfe_u32 v97, v129, 4, 2
	v_lshlrev_b32_e32 v97, 2, v97
	s_movk_i32 s14, 0x1600
	v_add3_u32 v97, v97, v152, s19
	v_mul_lo_u32 v98, v97, s14
	v_lshl_add_u32 v98, v96, 1, v98
	v_mul_f32_e32 v100, 0xbfb8aa3b, v0
	v_mul_f32_e32 v101, 0xbfb8aa3b, v1
	v_mul_f32_e32 v102, 0xbfb8aa3b, v2
	v_mul_f32_e32 v103, 0xbfb8aa3b, v3
	v_exp_f32_e32 v100, v100
	v_exp_f32_e32 v101, v101
	v_exp_f32_e32 v102, v102
	v_exp_f32_e32 v103, v103
	v_mov_b32_e32 v104, v98
	v_add_u32_e32 v105, 0x1600, v98
	v_add_u32_e32 v106, 0x2c00, v98
	v_add_u32_e32 v107, 0x4200, v98
	v_add_f32_e32 v100, 1.0, v100
	v_add_f32_e32 v101, 1.0, v101
	v_add_f32_e32 v102, 1.0, v102
	v_add_f32_e32 v103, 1.0, v103
	v_rcp_f32_e32 v100, v100
	v_rcp_f32_e32 v101, v101
	v_rcp_f32_e32 v102, v102
	v_rcp_f32_e32 v103, v103
	s_nop 0
	v_mul_f32_e32 v0, v0, v100
	v_mul_f32_e32 v1, v1, v101
	v_mul_f32_e32 v2, v2, v102
	v_mul_f32_e32 v3, v3, v103
	v_mul_f32_e32 v0, v8, v0
	v_mul_f32_e32 v1, v9, v1
	v_mul_f32_e32 v2, v10, v2
	v_mul_f32_e32 v3, v11, v3
	v_bfe_u32 v100, v0, 16, 1
	v_bfe_u32 v101, v1, 16, 1
	v_bfe_u32 v102, v2, 16, 1
	v_bfe_u32 v103, v3, 16, 1
	v_add3_u32 v0, v0, v100, s33
	v_add3_u32 v1, v1, v101, s33
	v_add3_u32 v2, v2, v102, s33
	v_add3_u32 v3, v3, v103, s33
	global_store_short_d16_hi v104, v0, s[4:5]
	global_store_short_d16_hi v105, v1, s[4:5]
	global_store_short_d16_hi v106, v2, s[4:5]
	global_store_short_d16_hi v107, v3, s[4:5]
	v_mul_f32_e32 v100, 0xbfb8aa3b, v4
	v_mul_f32_e32 v101, 0xbfb8aa3b, v5
	v_mul_f32_e32 v102, 0xbfb8aa3b, v6
	v_mul_f32_e32 v103, 0xbfb8aa3b, v7
	v_exp_f32_e32 v100, v100
	v_exp_f32_e32 v101, v101
	v_exp_f32_e32 v102, v102
	v_exp_f32_e32 v103, v103
	v_add_u32_e32 v104, 0x20, v98
	v_add_u32_e32 v105, 0x1620, v98
	v_add_u32_e32 v106, 0x2c20, v98
	v_add_u32_e32 v107, 0x4220, v98
	v_add_f32_e32 v100, 1.0, v100
	v_add_f32_e32 v101, 1.0, v101
	v_add_f32_e32 v102, 1.0, v102
	v_add_f32_e32 v103, 1.0, v103
	v_rcp_f32_e32 v100, v100
	v_rcp_f32_e32 v101, v101
	v_rcp_f32_e32 v102, v102
	v_rcp_f32_e32 v103, v103
	s_nop 0
	v_mul_f32_e32 v4, v4, v100
	v_mul_f32_e32 v5, v5, v101
	v_mul_f32_e32 v6, v6, v102
	v_mul_f32_e32 v7, v7, v103
	v_mul_f32_e32 v4, v12, v4
	v_mul_f32_e32 v5, v13, v5
	v_mul_f32_e32 v6, v14, v6
	v_mul_f32_e32 v7, v15, v7
	v_bfe_u32 v100, v4, 16, 1
	v_bfe_u32 v101, v5, 16, 1
	v_bfe_u32 v102, v6, 16, 1
	v_bfe_u32 v103, v7, 16, 1
	v_add3_u32 v4, v4, v100, s33
	v_add3_u32 v5, v5, v101, s33
	v_add3_u32 v6, v6, v102, s33
	v_add3_u32 v7, v7, v103, s33
	global_store_short_d16_hi v104, v4, s[4:5]
	global_store_short_d16_hi v105, v5, s[4:5]
	global_store_short_d16_hi v106, v6, s[4:5]
	global_store_short_d16_hi v107, v7, s[4:5]
	v_mul_f32_e32 v100, 0xbfb8aa3b, v16
	v_mul_f32_e32 v101, 0xbfb8aa3b, v17
	v_mul_f32_e32 v102, 0xbfb8aa3b, v18
	v_mul_f32_e32 v103, 0xbfb8aa3b, v19
	v_exp_f32_e32 v100, v100
	v_exp_f32_e32 v101, v101
	v_exp_f32_e32 v102, v102
	v_exp_f32_e32 v103, v103
	v_add_u32_e32 v104, 0x16000, v98
	v_add_u32_e32 v105, 0x17600, v98
	v_add_u32_e32 v106, 0x18c00, v98
	v_add_u32_e32 v107, 0x1a200, v98
	v_add_f32_e32 v100, 1.0, v100
	v_add_f32_e32 v101, 1.0, v101
	v_add_f32_e32 v102, 1.0, v102
	v_add_f32_e32 v103, 1.0, v103
	v_rcp_f32_e32 v100, v100
	v_rcp_f32_e32 v101, v101
	v_rcp_f32_e32 v102, v102
	v_rcp_f32_e32 v103, v103
	s_nop 0
	v_mul_f32_e32 v16, v16, v100
	v_mul_f32_e32 v17, v17, v101
	v_mul_f32_e32 v18, v18, v102
	v_mul_f32_e32 v19, v19, v103
	v_mul_f32_e32 v16, v24, v16
	v_mul_f32_e32 v17, v25, v17
	v_mul_f32_e32 v18, v26, v18
	v_mul_f32_e32 v19, v27, v19
	v_bfe_u32 v100, v16, 16, 1
	v_bfe_u32 v101, v17, 16, 1
	v_bfe_u32 v102, v18, 16, 1
	v_bfe_u32 v103, v19, 16, 1
	v_add3_u32 v16, v16, v100, s33
	v_add3_u32 v17, v17, v101, s33
	v_add3_u32 v18, v18, v102, s33
	v_add3_u32 v19, v19, v103, s33
	global_store_short_d16_hi v104, v16, s[4:5]
	global_store_short_d16_hi v105, v17, s[4:5]
	global_store_short_d16_hi v106, v18, s[4:5]
	global_store_short_d16_hi v107, v19, s[4:5]
	v_mul_f32_e32 v100, 0xbfb8aa3b, v20
	v_mul_f32_e32 v101, 0xbfb8aa3b, v21
	v_mul_f32_e32 v102, 0xbfb8aa3b, v22
	v_mul_f32_e32 v103, 0xbfb8aa3b, v23
	v_exp_f32_e32 v100, v100
	v_exp_f32_e32 v101, v101
	v_exp_f32_e32 v102, v102
	v_exp_f32_e32 v103, v103
	v_add_u32_e32 v104, 0x16020, v98
	v_add_u32_e32 v105, 0x17620, v98
	v_add_u32_e32 v106, 0x18c20, v98
	v_add_u32_e32 v107, 0x1a220, v98
	v_add_f32_e32 v100, 1.0, v100
	v_add_f32_e32 v101, 1.0, v101
	v_add_f32_e32 v102, 1.0, v102
	v_add_f32_e32 v103, 1.0, v103
	v_rcp_f32_e32 v100, v100
	v_rcp_f32_e32 v101, v101
	v_rcp_f32_e32 v102, v102
	v_rcp_f32_e32 v103, v103
	s_nop 0
	v_mul_f32_e32 v20, v20, v100
	v_mul_f32_e32 v21, v21, v101
	v_mul_f32_e32 v22, v22, v102
	v_mul_f32_e32 v23, v23, v103
	v_mul_f32_e32 v20, v28, v20
	v_mul_f32_e32 v21, v29, v21
	v_mul_f32_e32 v22, v30, v22
	v_mul_f32_e32 v23, v31, v23
	v_bfe_u32 v100, v20, 16, 1
	v_bfe_u32 v101, v21, 16, 1
	v_bfe_u32 v102, v22, 16, 1
	v_bfe_u32 v103, v23, 16, 1
	v_add3_u32 v20, v20, v100, s33
	v_add3_u32 v21, v21, v101, s33
	v_add3_u32 v22, v22, v102, s33
	v_add3_u32 v23, v23, v103, s33
	global_store_short_d16_hi v104, v20, s[4:5]
	global_store_short_d16_hi v105, v21, s[4:5]
	global_store_short_d16_hi v106, v22, s[4:5]
	global_store_short_d16_hi v107, v23, s[4:5]
	v_mul_f32_e32 v100, 0xbfb8aa3b, v32
	v_mul_f32_e32 v101, 0xbfb8aa3b, v33
	v_mul_f32_e32 v102, 0xbfb8aa3b, v34
	v_mul_f32_e32 v103, 0xbfb8aa3b, v35
	v_exp_f32_e32 v100, v100
	v_exp_f32_e32 v101, v101
	v_exp_f32_e32 v102, v102
	v_exp_f32_e32 v103, v103
	v_add_u32_e32 v104, 0x2c000, v98
	v_add_u32_e32 v105, 0x2d600, v98
	v_add_u32_e32 v106, 0x2ec00, v98
	v_add_u32_e32 v107, 0x30200, v98
	v_add_f32_e32 v100, 1.0, v100
	v_add_f32_e32 v101, 1.0, v101
	v_add_f32_e32 v102, 1.0, v102
	v_add_f32_e32 v103, 1.0, v103
	v_rcp_f32_e32 v100, v100
	v_rcp_f32_e32 v101, v101
	v_rcp_f32_e32 v102, v102
	v_rcp_f32_e32 v103, v103
	s_nop 0
	v_mul_f32_e32 v32, v32, v100
	v_mul_f32_e32 v33, v33, v101
	v_mul_f32_e32 v34, v34, v102
	v_mul_f32_e32 v35, v35, v103
	v_mul_f32_e32 v32, v40, v32
	v_mul_f32_e32 v33, v41, v33
	v_mul_f32_e32 v34, v42, v34
	v_mul_f32_e32 v35, v43, v35
	v_bfe_u32 v100, v32, 16, 1
	v_bfe_u32 v101, v33, 16, 1
	v_bfe_u32 v102, v34, 16, 1
	v_bfe_u32 v103, v35, 16, 1
	v_add3_u32 v32, v32, v100, s33
	v_add3_u32 v33, v33, v101, s33
	v_add3_u32 v34, v34, v102, s33
	v_add3_u32 v35, v35, v103, s33
	global_store_short_d16_hi v104, v32, s[4:5]
	global_store_short_d16_hi v105, v33, s[4:5]
	global_store_short_d16_hi v106, v34, s[4:5]
	global_store_short_d16_hi v107, v35, s[4:5]
	v_mul_f32_e32 v100, 0xbfb8aa3b, v36
	v_mul_f32_e32 v101, 0xbfb8aa3b, v37
	v_mul_f32_e32 v102, 0xbfb8aa3b, v38
	v_mul_f32_e32 v103, 0xbfb8aa3b, v39
	v_exp_f32_e32 v100, v100
	v_exp_f32_e32 v101, v101
	v_exp_f32_e32 v102, v102
	v_exp_f32_e32 v103, v103
	v_add_u32_e32 v104, 0x2c020, v98
	v_add_u32_e32 v105, 0x2d620, v98
	v_add_u32_e32 v106, 0x2ec20, v98
	v_add_u32_e32 v107, 0x30220, v98
	v_add_f32_e32 v100, 1.0, v100
	v_add_f32_e32 v101, 1.0, v101
	v_add_f32_e32 v102, 1.0, v102
	v_add_f32_e32 v103, 1.0, v103
	v_rcp_f32_e32 v100, v100
	v_rcp_f32_e32 v101, v101
	v_rcp_f32_e32 v102, v102
	v_rcp_f32_e32 v103, v103
	s_nop 0
	v_mul_f32_e32 v36, v36, v100
	v_mul_f32_e32 v37, v37, v101
	v_mul_f32_e32 v38, v38, v102
	v_mul_f32_e32 v39, v39, v103
	v_mul_f32_e32 v36, v44, v36
	v_mul_f32_e32 v37, v45, v37
	v_mul_f32_e32 v38, v46, v38
	v_mul_f32_e32 v39, v47, v39
	v_bfe_u32 v100, v36, 16, 1
	v_bfe_u32 v101, v37, 16, 1
	v_bfe_u32 v102, v38, 16, 1
	v_bfe_u32 v103, v39, 16, 1
	v_add3_u32 v36, v36, v100, s33
	v_add3_u32 v37, v37, v101, s33
	v_add3_u32 v38, v38, v102, s33
	v_add3_u32 v39, v39, v103, s33
	global_store_short_d16_hi v104, v36, s[4:5]
	global_store_short_d16_hi v105, v37, s[4:5]
	global_store_short_d16_hi v106, v38, s[4:5]
	global_store_short_d16_hi v107, v39, s[4:5]
	v_mul_f32_e32 v100, 0xbfb8aa3b, v48
	v_mul_f32_e32 v101, 0xbfb8aa3b, v49
	v_mul_f32_e32 v102, 0xbfb8aa3b, v50
	v_mul_f32_e32 v103, 0xbfb8aa3b, v51
	v_exp_f32_e32 v100, v100
	v_exp_f32_e32 v101, v101
	v_exp_f32_e32 v102, v102
	v_exp_f32_e32 v103, v103
	v_add_u32_e32 v104, 0x42000, v98
	v_add_u32_e32 v105, 0x43600, v98
	v_add_u32_e32 v106, 0x44c00, v98
	v_add_u32_e32 v107, 0x46200, v98
	v_add_f32_e32 v100, 1.0, v100
	v_add_f32_e32 v101, 1.0, v101
	v_add_f32_e32 v102, 1.0, v102
	v_add_f32_e32 v103, 1.0, v103
	v_rcp_f32_e32 v100, v100
	v_rcp_f32_e32 v101, v101
	v_rcp_f32_e32 v102, v102
	v_rcp_f32_e32 v103, v103
	s_nop 0
	v_mul_f32_e32 v48, v48, v100
	v_mul_f32_e32 v49, v49, v101
	v_mul_f32_e32 v50, v50, v102
	v_mul_f32_e32 v51, v51, v103
	v_mul_f32_e32 v48, v56, v48
	v_mul_f32_e32 v49, v57, v49
	v_mul_f32_e32 v50, v58, v50
	v_mul_f32_e32 v51, v59, v51
	v_bfe_u32 v100, v48, 16, 1
	v_bfe_u32 v101, v49, 16, 1
	v_bfe_u32 v102, v50, 16, 1
	v_bfe_u32 v103, v51, 16, 1
	v_add3_u32 v48, v48, v100, s33
	v_add3_u32 v49, v49, v101, s33
	v_add3_u32 v50, v50, v102, s33
	v_add3_u32 v51, v51, v103, s33
	global_store_short_d16_hi v104, v48, s[4:5]
	global_store_short_d16_hi v105, v49, s[4:5]
	global_store_short_d16_hi v106, v50, s[4:5]
	global_store_short_d16_hi v107, v51, s[4:5]
	v_mul_f32_e32 v100, 0xbfb8aa3b, v52
	v_mul_f32_e32 v101, 0xbfb8aa3b, v53
	v_mul_f32_e32 v102, 0xbfb8aa3b, v54
	v_mul_f32_e32 v103, 0xbfb8aa3b, v55
	v_exp_f32_e32 v100, v100
	v_exp_f32_e32 v101, v101
	v_exp_f32_e32 v102, v102
	v_exp_f32_e32 v103, v103
	v_add_u32_e32 v104, 0x42020, v98
	v_add_u32_e32 v105, 0x43620, v98
	v_add_u32_e32 v106, 0x44c20, v98
	v_add_u32_e32 v107, 0x46220, v98
	v_add_f32_e32 v100, 1.0, v100
	v_add_f32_e32 v101, 1.0, v101
	v_add_f32_e32 v102, 1.0, v102
	v_add_f32_e32 v103, 1.0, v103
	v_rcp_f32_e32 v100, v100
	v_rcp_f32_e32 v101, v101
	v_rcp_f32_e32 v102, v102
	v_rcp_f32_e32 v103, v103
	s_nop 0
	v_mul_f32_e32 v52, v52, v100
	v_mul_f32_e32 v53, v53, v101
	v_mul_f32_e32 v54, v54, v102
	v_mul_f32_e32 v55, v55, v103
	v_mul_f32_e32 v52, v60, v52
	v_mul_f32_e32 v53, v61, v53
	v_mul_f32_e32 v54, v62, v54
	v_mul_f32_e32 v55, v63, v55
	v_bfe_u32 v100, v52, 16, 1
	v_bfe_u32 v101, v53, 16, 1
	v_bfe_u32 v102, v54, 16, 1
	v_bfe_u32 v103, v55, 16, 1
	v_add3_u32 v52, v52, v100, s33
	v_add3_u32 v53, v53, v101, s33
	v_add3_u32 v54, v54, v102, s33
	v_add3_u32 v55, v55, v103, s33
	global_store_short_d16_hi v104, v52, s[4:5]
	global_store_short_d16_hi v105, v53, s[4:5]
	global_store_short_d16_hi v106, v54, s[4:5]
	global_store_short_d16_hi v107, v55, s[4:5]
	v_mul_f32_e32 v100, 0xbfb8aa3b, v64
	v_mul_f32_e32 v101, 0xbfb8aa3b, v65
	v_mul_f32_e32 v102, 0xbfb8aa3b, v66
	v_mul_f32_e32 v103, 0xbfb8aa3b, v67
	v_exp_f32_e32 v100, v100
	v_exp_f32_e32 v101, v101
	v_exp_f32_e32 v102, v102
	v_exp_f32_e32 v103, v103
	v_add_u32_e32 v104, 0x58000, v98
	v_add_u32_e32 v105, 0x59600, v98
	v_add_u32_e32 v106, 0x5ac00, v98
	v_add_u32_e32 v107, 0x5c200, v98
	v_add_f32_e32 v100, 1.0, v100
	v_add_f32_e32 v101, 1.0, v101
	v_add_f32_e32 v102, 1.0, v102
	v_add_f32_e32 v103, 1.0, v103
	v_rcp_f32_e32 v100, v100
	v_rcp_f32_e32 v101, v101
	v_rcp_f32_e32 v102, v102
	v_rcp_f32_e32 v103, v103
	s_nop 0
	v_mul_f32_e32 v64, v64, v100
	v_mul_f32_e32 v65, v65, v101
	v_mul_f32_e32 v66, v66, v102
	v_mul_f32_e32 v67, v67, v103
	v_mul_f32_e32 v64, v72, v64
	v_mul_f32_e32 v65, v73, v65
	v_mul_f32_e32 v66, v74, v66
	v_mul_f32_e32 v67, v75, v67
	v_bfe_u32 v100, v64, 16, 1
	v_bfe_u32 v101, v65, 16, 1
	v_bfe_u32 v102, v66, 16, 1
	v_bfe_u32 v103, v67, 16, 1
	v_add3_u32 v64, v64, v100, s33
	v_add3_u32 v65, v65, v101, s33
	v_add3_u32 v66, v66, v102, s33
	v_add3_u32 v67, v67, v103, s33
	global_store_short_d16_hi v104, v64, s[4:5]
	global_store_short_d16_hi v105, v65, s[4:5]
	global_store_short_d16_hi v106, v66, s[4:5]
	global_store_short_d16_hi v107, v67, s[4:5]
	v_mul_f32_e32 v100, 0xbfb8aa3b, v68
	v_mul_f32_e32 v101, 0xbfb8aa3b, v69
	v_mul_f32_e32 v102, 0xbfb8aa3b, v70
	v_mul_f32_e32 v103, 0xbfb8aa3b, v71
	v_exp_f32_e32 v100, v100
	v_exp_f32_e32 v101, v101
	v_exp_f32_e32 v102, v102
	v_exp_f32_e32 v103, v103
	v_add_u32_e32 v104, 0x58020, v98
	v_add_u32_e32 v105, 0x59620, v98
	v_add_u32_e32 v106, 0x5ac20, v98
	v_add_u32_e32 v107, 0x5c220, v98
	v_add_f32_e32 v100, 1.0, v100
	v_add_f32_e32 v101, 1.0, v101
	v_add_f32_e32 v102, 1.0, v102
	v_add_f32_e32 v103, 1.0, v103
	v_rcp_f32_e32 v100, v100
	v_rcp_f32_e32 v101, v101
	v_rcp_f32_e32 v102, v102
	v_rcp_f32_e32 v103, v103
	s_nop 0
	v_mul_f32_e32 v68, v68, v100
	v_mul_f32_e32 v69, v69, v101
	v_mul_f32_e32 v70, v70, v102
	v_mul_f32_e32 v71, v71, v103
	v_mul_f32_e32 v68, v76, v68
	v_mul_f32_e32 v69, v77, v69
	v_mul_f32_e32 v70, v78, v70
	v_mul_f32_e32 v71, v79, v71
	v_bfe_u32 v100, v68, 16, 1
	v_bfe_u32 v101, v69, 16, 1
	v_bfe_u32 v102, v70, 16, 1
	v_bfe_u32 v103, v71, 16, 1
	v_add3_u32 v68, v68, v100, s33
	v_add3_u32 v69, v69, v101, s33
	v_add3_u32 v70, v70, v102, s33
	v_add3_u32 v71, v71, v103, s33
	global_store_short_d16_hi v104, v68, s[4:5]
	global_store_short_d16_hi v105, v69, s[4:5]
	global_store_short_d16_hi v106, v70, s[4:5]
	global_store_short_d16_hi v107, v71, s[4:5]
	v_mul_f32_e32 v100, 0xbfb8aa3b, v80
	v_mul_f32_e32 v101, 0xbfb8aa3b, v81
	v_mul_f32_e32 v102, 0xbfb8aa3b, v82
	v_mul_f32_e32 v103, 0xbfb8aa3b, v83
	v_exp_f32_e32 v100, v100
	v_exp_f32_e32 v101, v101
	v_exp_f32_e32 v102, v102
	v_exp_f32_e32 v103, v103
	v_add_u32_e32 v104, 0x6e000, v98
	v_add_u32_e32 v105, 0x6f600, v98
	v_add_u32_e32 v106, 0x70c00, v98
	v_add_u32_e32 v107, 0x72200, v98
	v_add_f32_e32 v100, 1.0, v100
	v_add_f32_e32 v101, 1.0, v101
	v_add_f32_e32 v102, 1.0, v102
	v_add_f32_e32 v103, 1.0, v103
	v_rcp_f32_e32 v100, v100
	v_rcp_f32_e32 v101, v101
	v_rcp_f32_e32 v102, v102
	v_rcp_f32_e32 v103, v103
	s_nop 0
	v_mul_f32_e32 v80, v80, v100
	v_mul_f32_e32 v81, v81, v101
	v_mul_f32_e32 v82, v82, v102
	v_mul_f32_e32 v83, v83, v103
	v_mul_f32_e32 v80, v88, v80
	v_mul_f32_e32 v81, v89, v81
	v_mul_f32_e32 v82, v90, v82
	v_mul_f32_e32 v83, v91, v83
	v_bfe_u32 v100, v80, 16, 1
	v_bfe_u32 v101, v81, 16, 1
	v_bfe_u32 v102, v82, 16, 1
	v_bfe_u32 v103, v83, 16, 1
	v_add3_u32 v80, v80, v100, s33
	v_add3_u32 v81, v81, v101, s33
	v_add3_u32 v82, v82, v102, s33
	v_add3_u32 v83, v83, v103, s33
	global_store_short_d16_hi v104, v80, s[4:5]
	global_store_short_d16_hi v105, v81, s[4:5]
	global_store_short_d16_hi v106, v82, s[4:5]
	global_store_short_d16_hi v107, v83, s[4:5]
	v_mul_f32_e32 v100, 0xbfb8aa3b, v84
	v_mul_f32_e32 v101, 0xbfb8aa3b, v85
	v_mul_f32_e32 v102, 0xbfb8aa3b, v86
	v_mul_f32_e32 v103, 0xbfb8aa3b, v87
	v_exp_f32_e32 v100, v100
	v_exp_f32_e32 v101, v101
	v_exp_f32_e32 v102, v102
	v_exp_f32_e32 v103, v103
	v_add_u32_e32 v104, 0x6e020, v98
	v_add_u32_e32 v105, 0x6f620, v98
	v_add_u32_e32 v106, 0x70c20, v98
	v_add_u32_e32 v107, 0x72220, v98
	v_add_f32_e32 v100, 1.0, v100
	v_add_f32_e32 v101, 1.0, v101
	v_add_f32_e32 v102, 1.0, v102
	v_add_f32_e32 v103, 1.0, v103
	v_rcp_f32_e32 v100, v100
	v_rcp_f32_e32 v101, v101
	v_rcp_f32_e32 v102, v102
	v_rcp_f32_e32 v103, v103
	s_nop 0
	v_mul_f32_e32 v84, v84, v100
	v_mul_f32_e32 v85, v85, v101
	v_mul_f32_e32 v86, v86, v102
	v_mul_f32_e32 v87, v87, v103
	v_mul_f32_e32 v84, v92, v84
	v_mul_f32_e32 v85, v93, v85
	v_mul_f32_e32 v86, v94, v86
	v_mul_f32_e32 v87, v95, v87
	v_bfe_u32 v100, v84, 16, 1
	v_bfe_u32 v101, v85, 16, 1
	v_bfe_u32 v102, v86, 16, 1
	v_bfe_u32 v103, v87, 16, 1
	v_add3_u32 v84, v84, v100, s33
	v_add3_u32 v85, v85, v101, s33
	v_add3_u32 v86, v86, v102, s33
	v_add3_u32 v87, v87, v103, s33
	global_store_short_d16_hi v104, v84, s[4:5]
	global_store_short_d16_hi v105, v85, s[4:5]
	global_store_short_d16_hi v106, v86, s[4:5]
	global_store_short_d16_hi v107, v87, s[4:5]
	s_add_i32 s18, s18, s76
	s_cmpk_gt_i32 s18, 0x57f
	s_cbranch_scc1 .LBB0_87
.LBB0_83:
	s_ashr_i32 s14, s18, 31
	v_mov_b32_e32 v129, v127
	s_lshr_b32 s14, s14, 27
	s_add_i32 s14, s18, s14
	s_waitcnt vmcnt(6)
	v_ashrrev_i32_e32 v20, 6, v129
	s_waitcnt vmcnt(5)
	v_bfe_u32 v24, v129, 3, 3
	v_lshlrev_b32_e32 v25, 3, v20
	s_ashr_i32 s20, s14, 5
	s_and_b32 s14, s14, 0x3ffffe0
	v_or_b32_e32 v12, v25, v24
	s_sub_i32 s19, s18, s14
	v_lshrrev_b32_e32 v26, 1, v12
	s_mulk_i32 s19, 0xc0
	v_lshrrev_b32_e32 v0, 31, v129
	v_xor_b32_e32 v2, v26, v129
	v_add_u32_e32 v21, v20, v0
	v_and_b32_e32 v23, 63, v129
	v_add_u32_e32 v0, s19, v12
	v_lshlrev_b32_e32 v2, 4, v2
	v_add_u32_e32 v14, 32, v12
	v_ashrrev_i32_e32 v1, 31, v0
	v_and_b32_e32 v124, 0x70, v2
	v_add_u32_e32 v2, s19, v14
	v_add_u32_e32 v16, 64, v12
	s_add_i32 s15, s19, 0x80
	v_lshlrev_b32_e32 v23, 4, v23
	v_lshlrev_b64 v[0:1], 11, v[0:1]
	v_ashrrev_i32_e32 v3, 31, v2
	v_add_u32_e32 v4, s19, v16
	v_add_u32_e32 v18, 0x60, v12
	v_add_u32_e32 v8, s15, v12
	s_add_i32 s15, s19, 0xa0
	v_lshl_or_b32 v142, v20, 10, v23
	v_lshl_add_u64 v[0:1], s[6:7], 0, v[0:1]
	v_lshlrev_b64 v[2:3], 11, v[2:3]
	v_ashrrev_i32_e32 v5, 31, v4
	v_add_u32_e32 v6, s19, v18
	v_add_u32_e32 v10, s15, v12
	v_readfirstlane_b32 s15, v142
	v_add_u32_e32 v144, 0x1000, v142
	v_lshl_add_u64 v[0:1], v[0:1], 0, v[124:125]
	v_lshl_add_u64 v[2:3], s[6:7], 0, v[2:3]
	v_lshlrev_b64 v[4:5], 11, v[4:5]
	v_ashrrev_i32_e32 v7, 31, v6
	s_mov_b32 m0, s15
	v_readfirstlane_b32 s15, v144
	v_add_u32_e32 v145, 0x2000, v142
	s_lshl_b32 s14, s20, 7
	v_lshl_add_u64 v[2:3], v[2:3], 0, v[124:125]
	v_lshl_add_u64 v[4:5], s[6:7], 0, v[4:5]
	v_lshlrev_b64 v[6:7], 11, v[6:7]
	v_ashrrev_i32_e32 v9, 31, v8
	global_load_lds_dwordx4 v[0:1], off
	s_mov_b32 m0, s15
	v_readfirstlane_b32 s15, v145
	v_add_u32_e32 v146, 0x3000, v142
	v_lshl_add_u64 v[4:5], v[4:5], 0, v[124:125]
	v_lshl_add_u64 v[6:7], s[6:7], 0, v[6:7]
	v_lshlrev_b64 v[8:9], 11, v[8:9]
	v_ashrrev_i32_e32 v11, 31, v10
	v_add_u32_e32 v12, s14, v12
	global_load_lds_dwordx4 v[2:3], off
	s_mov_b32 m0, s15
	v_readfirstlane_b32 s15, v146
	v_add_u32_e32 v147, 0x4000, v142
	v_lshl_add_u64 v[6:7], v[6:7], 0, v[124:125]
	v_lshl_add_u64 v[8:9], s[6:7], 0, v[8:9]
	v_lshlrev_b64 v[10:11], 11, v[10:11]
	v_ashrrev_i32_e32 v13, 31, v12
	v_add_u32_e32 v14, s14, v14
	global_load_lds_dwordx4 v[4:5], off
	s_mov_b32 m0, s15
	v_readfirstlane_b32 s15, v147
	v_add_u32_e32 v148, 0x5000, v142
	v_lshl_add_u64 v[8:9], v[8:9], 0, v[124:125]
	v_lshl_add_u64 v[10:11], s[6:7], 0, v[10:11]
	v_lshlrev_b64 v[12:13], 11, v[12:13]
	v_ashrrev_i32_e32 v15, 31, v14
	v_add_u32_e32 v16, s14, v16
	v_add_u32_e32 v143, 0xc000, v142
	global_load_lds_dwordx4 v[6:7], off
	s_mov_b32 m0, s15
	v_readfirstlane_b32 s15, v148
	v_lshl_add_u64 v[10:11], v[10:11], 0, v[124:125]
	v_lshl_add_u64 v[12:13], s[12:13], 0, v[12:13]
	v_lshlrev_b64 v[14:15], 11, v[14:15]
	v_ashrrev_i32_e32 v17, 31, v16
	v_add_u32_e32 v18, s14, v18
	global_load_lds_dwordx4 v[8:9], off
	s_mov_b32 m0, s15
	v_readfirstlane_b32 s15, v143
	v_add_u32_e32 v150, 0xd000, v142
	v_lshl_add_u64 v[12:13], v[12:13], 0, v[124:125]
	v_lshl_add_u64 v[14:15], s[12:13], 0, v[14:15]
	v_lshlrev_b64 v[16:17], 11, v[16:17]
	v_ashrrev_i32_e32 v19, 31, v18
	global_load_lds_dwordx4 v[10:11], off
	s_mov_b32 m0, s15
	v_readfirstlane_b32 s15, v150
	v_add_u32_e32 v153, 0xe000, v142
	v_lshl_add_u64 v[14:15], v[14:15], 0, v[124:125]
	v_lshl_add_u64 v[16:17], s[12:13], 0, v[16:17]
	v_lshlrev_b64 v[18:19], 11, v[18:19]
	global_load_lds_dwordx4 v[12:13], off
	s_mov_b32 m0, s15
	v_readfirstlane_b32 s15, v153
	v_add_u32_e32 v154, 0xf000, v142
	v_lshl_add_u64 v[16:17], v[16:17], 0, v[124:125]
	v_lshl_add_u64 v[18:19], s[12:13], 0, v[18:19]
	global_load_lds_dwordx4 v[14:15], off
	s_mov_b32 m0, s15
	v_readfirstlane_b32 s15, v154
	v_lshl_add_u64 v[18:19], v[18:19], 0, v[124:125]
	global_load_lds_dwordx4 v[16:17], off
	s_mov_b32 m0, s15
	v_lshrrev_b32_e32 v22, 1, v21
	global_load_lds_dwordx4 v[18:19], off
	v_and_b32_e32 v149, 31, v129
	v_mul_lo_u32 v152, v22, s80
	v_and_b32_e32 v0, -2, v21
	v_or_b32_e32 v1, v152, v149
	v_sub_u32_e32 v151, v20, v0
	v_lshlrev_b32_e32 v155, 7, v1
	v_lshlrev_b32_e32 v1, 7, v149
	v_lshrrev_b32_e32 v23, 1, v129
	v_lshl_or_b32 v182, v151, 13, v1
	v_bfe_u32 v1, v129, 5, 1
	v_bfe_u32 v0, v129, 1, 3
	v_bitop3_b32 v2, v1, v23, 7 bitop3:0x78
	v_lshlrev_b32_e32 v184, 4, v2
	v_bitop3_b32 v2, v1, v0, 2 bitop3:0x36
	v_lshlrev_b32_e32 v185, 4, v2
	v_bitop3_b32 v2, v1, v0, 4 bitop3:0x36
	v_bitop3_b32 v0, v1, v0, 6 bitop3:0x36
	v_lshlrev_b32_e32 v187, 4, v0
	v_bitop3_b32 v0, v26, 7, v129 bitop3:0x48
	s_mul_i32 s15, s18, 0xc0
	v_lshlrev_b32_e32 v124, 4, v0
	v_or_b32_e32 v0, s15, v24
	v_add_u32_e32 v0, v0, v25
	s_mul_i32 s21, s20, 0x1800
	v_subrev_u32_e32 v0, s21, v0
	v_ashrrev_i32_e32 v1, 31, v0
	v_or_b32_e32 v4, 32, v24
	v_lshlrev_b32_e32 v186, 4, v2
	v_lshlrev_b64 v[2:3], 11, v[0:1]
	v_or_b32_e32 v1, s15, v4
	v_add_u32_e32 v1, v1, v25
	v_lshl_add_u64 v[96:97], s[6:7], 0, v[2:3]
	v_subrev_u32_e32 v2, s21, v1
	v_ashrrev_i32_e32 v3, 31, v2
	v_or_b32_e32 v5, 64, v24
	v_lshlrev_b64 v[2:3], 11, v[2:3]
	v_add3_u32 v1, v5, s15, v25
	v_lshl_add_u64 v[98:99], s[6:7], 0, v[2:3]
	v_subrev_u32_e32 v2, s21, v1
	v_ashrrev_i32_e32 v3, 31, v2
	v_or_b32_e32 v6, 0x60, v24
	v_lshlrev_b64 v[2:3], 11, v[2:3]
	v_add3_u32 v1, v6, s15, v25
	v_lshl_add_u64 v[100:101], s[6:7], 0, v[2:3]
	v_subrev_u32_e32 v2, s21, v1
	v_ashrrev_i32_e32 v3, 31, v2
	v_lshlrev_b64 v[2:3], 11, v[2:3]
	v_lshl_add_u64 v[102:103], s[6:7], 0, v[2:3]
	v_add_u32_e32 v2, 0x80, v0
	v_add_u32_e32 v0, 0xa0, v0
	v_ashrrev_i32_e32 v1, 31, v0
	v_lshlrev_b64 v[0:1], 11, v[0:1]
	v_lshl_add_u64 v[106:107], s[6:7], 0, v[0:1]
	v_or_b32_e32 v0, s14, v24
	v_add_u32_e32 v0, v0, v25
	v_ashrrev_i32_e32 v1, 31, v0
	v_lshlrev_b64 v[0:1], 11, v[0:1]
	v_lshl_add_u64 v[108:109], s[10:11], 0, v[0:1]
	v_or_b32_e32 v0, s14, v4
	v_add_u32_e32 v0, v0, v25
	v_ashrrev_i32_e32 v1, 31, v0
	v_lshlrev_b64 v[0:1], 11, v[0:1]
	v_lshl_add_u64 v[110:111], s[10:11], 0, v[0:1]
	v_or_b32_e32 v0, s14, v5
	v_add_u32_e32 v0, v0, v25
	v_ashrrev_i32_e32 v1, 31, v0
	v_lshlrev_b64 v[0:1], 11, v[0:1]
	v_lshl_add_u64 v[112:113], s[10:11], 0, v[0:1]
	v_or_b32_e32 v0, s14, v6
	v_add_u32_e32 v0, v0, v25
	s_waitcnt vmcnt(0)
	v_ashrrev_i32_e32 v3, 31, v2
	v_ashrrev_i32_e32 v1, 31, v0
	v_lshlrev_b64 v[2:3], 11, v[2:3]
	v_lshlrev_b64 v[0:1], 11, v[0:1]
	v_mov_b32_e32 v64, 0
	v_add_u32_e32 v183, 0x10000, v182
	v_lshl_add_u64 v[104:105], s[6:7], 0, v[2:3]
	v_lshl_add_u64 v[114:115], s[10:11], 0, v[0:1]
	s_mov_b32 s21, 0
	v_mov_b32_e32 v65, v64
	v_mov_b32_e32 v66, v64
	v_mov_b32_e32 v67, v64
	v_mov_b32_e32 v68, v64
	v_mov_b32_e32 v69, v64
	v_mov_b32_e32 v70, v64
	v_mov_b32_e32 v71, v64
	v_mov_b32_e32 v72, v64
	v_mov_b32_e32 v73, v64
	v_mov_b32_e32 v74, v64
	v_mov_b32_e32 v75, v64
	v_mov_b32_e32 v76, v64
	v_mov_b32_e32 v77, v64
	v_mov_b32_e32 v78, v64
	v_mov_b32_e32 v79, v64
	v_mov_b32_e32 v80, v64
	v_mov_b32_e32 v81, v64
	v_mov_b32_e32 v82, v64
	v_mov_b32_e32 v83, v64
	v_mov_b32_e32 v84, v64
	v_mov_b32_e32 v85, v64
	v_mov_b32_e32 v86, v64
	v_mov_b32_e32 v87, v64
	v_mov_b32_e32 v88, v64
	v_mov_b32_e32 v89, v64
	v_mov_b32_e32 v90, v64
	v_mov_b32_e32 v91, v64
	v_mov_b32_e32 v92, v64
	v_mov_b32_e32 v93, v64
	v_mov_b32_e32 v94, v64
	v_mov_b32_e32 v95, v64
	v_mov_b32_e32 v32, v64
	v_mov_b32_e32 v33, v64
	v_mov_b32_e32 v34, v64
	v_mov_b32_e32 v35, v64
	v_mov_b32_e32 v36, v64
	v_mov_b32_e32 v37, v64
	v_mov_b32_e32 v38, v64
	v_mov_b32_e32 v39, v64
	v_mov_b32_e32 v40, v64
	v_mov_b32_e32 v41, v64
	v_mov_b32_e32 v42, v64
	v_mov_b32_e32 v43, v64
	v_mov_b32_e32 v44, v64
	v_mov_b32_e32 v45, v64
	v_mov_b32_e32 v46, v64
	v_mov_b32_e32 v47, v64
	v_mov_b32_e32 v48, v64
	v_mov_b32_e32 v49, v64
	v_mov_b32_e32 v50, v64
	v_mov_b32_e32 v51, v64
	v_mov_b32_e32 v52, v64
	v_mov_b32_e32 v53, v64
	v_mov_b32_e32 v54, v64
	v_mov_b32_e32 v55, v64
	v_mov_b32_e32 v56, v64
	v_mov_b32_e32 v57, v64
	v_mov_b32_e32 v58, v64
	v_mov_b32_e32 v59, v64
	v_mov_b32_e32 v60, v64
	v_mov_b32_e32 v61, v64
	v_mov_b32_e32 v62, v64
	v_mov_b32_e32 v63, v64
	v_mov_b32_e32 v0, v64
	v_mov_b32_e32 v1, v64
	v_mov_b32_e32 v2, v64
	v_mov_b32_e32 v3, v64
	v_mov_b32_e32 v4, v64
	v_mov_b32_e32 v5, v64
	v_mov_b32_e32 v6, v64
	v_mov_b32_e32 v7, v64
	v_mov_b32_e32 v8, v64
	v_mov_b32_e32 v9, v64
	v_mov_b32_e32 v10, v64
	v_mov_b32_e32 v11, v64
	v_mov_b32_e32 v12, v64
	v_mov_b32_e32 v13, v64
	v_mov_b32_e32 v14, v64
	v_mov_b32_e32 v15, v64
	v_mov_b32_e32 v16, v64
	v_mov_b32_e32 v17, v64
	v_mov_b32_e32 v18, v64
	v_mov_b32_e32 v19, v64
	v_mov_b32_e32 v20, v64
	v_mov_b32_e32 v21, v64
	v_mov_b32_e32 v22, v64
	v_mov_b32_e32 v23, v64
	v_mov_b32_e32 v24, v64
	v_mov_b32_e32 v25, v64
	v_mov_b32_e32 v26, v64
	v_mov_b32_e32 v27, v64
	s_waitcnt vmcnt(0)
	v_mov_b32_e32 v28, v64
	v_mov_b32_e32 v29, v64
	v_mov_b32_e32 v30, v64
	v_mov_b32_e32 v31, v64
	s_waitcnt vmcnt(0) lgkmcnt(0)
	s_barrier
	v_readfirstlane_b32 s101, v142
	s_sub_u32 vcc_lo, s12, s10
	s_subb_u32 vcc_hi, s13, s11
	v_mov_b32_e32 v130, v124
	v_mov_b32_e32 v131, 0
	v_lshl_add_u64 v[108:109], v[108:109], 0, vcc
	v_lshl_add_u64 v[110:111], v[110:111], 0, vcc
	v_lshl_add_u64 v[112:113], v[112:113], 0, vcc
	v_lshl_add_u64 v[114:115], v[114:115], 0, vcc
	v_lshl_add_u64 v[96:97], v[96:97], 0, v[130:131]
	v_lshl_add_u64 v[98:99], v[98:99], 0, v[130:131]
	v_lshl_add_u64 v[100:101], v[100:101], 0, v[130:131]
	v_lshl_add_u64 v[102:103], v[102:103], 0, v[130:131]
	v_lshl_add_u64 v[104:105], v[104:105], 0, v[130:131]
	v_lshl_add_u64 v[106:107], v[106:107], 0, v[130:131]
	v_lshl_add_u64 v[108:109], v[108:109], 0, v[130:131]
	v_lshl_add_u64 v[110:111], v[110:111], 0, v[130:131]
	v_lshl_add_u64 v[112:113], v[112:113], 0, v[130:131]
	v_lshl_add_u64 v[114:115], v[114:115], 0, v[130:131]
	v_and_b32_e32 v130, 15, v129
	v_bfe_u32 v131, v129, 4, 2
	v_bfe_u32 v116, v129, 1, 3
	v_xor_b32_e32 v117, v131, v116
	v_lshlrev_b32_e32 v117, 4, v117
	v_xor_b32_e32 v118, 64, v117
	v_lshrrev_b32_e32 v119, 7, v129
	v_mul_u32_u24_e32 v119, 0x60, v119
	v_add_u32_e32 v119, v119, v130
	v_lshlrev_b32_e32 v119, 7, v119
	v_bfe_u32 v120, v129, 6, 1
	v_lshl_add_u32 v120, v120, 6, v130
	v_lshlrev_b32_e32 v120, 7, v120
	v_add_u32_e32 v120, 0x8000, v120
	v_add_u32_e32 v150, v119, v117
	v_add_u32_e32 v153, v119, v118
	v_add_u32_e32 v154, v120, v117
	v_add_u32_e32 v155, v120, v118
	v_lshl_add_u64 v[96:97], v[96:97], 0, s[2:3]
	v_lshl_add_u64 v[98:99], v[98:99], 0, s[2:3]
	v_lshl_add_u64 v[100:101], v[100:101], 0, s[2:3]
	v_lshl_add_u64 v[102:103], v[102:103], 0, s[2:3]
	v_lshl_add_u64 v[104:105], v[104:105], 0, s[2:3]
	v_lshl_add_u64 v[106:107], v[106:107], 0, s[2:3]
	v_lshl_add_u64 v[108:109], v[108:109], 0, s[2:3]
	v_lshl_add_u64 v[110:111], v[110:111], 0, s[2:3]
	v_lshl_add_u64 v[112:113], v[112:113], 0, s[2:3]
	v_lshl_add_u64 v[114:115], v[114:115], 0, s[2:3]
	ds_read_b128 v[182:185], v150 offset:0
	ds_read_b128 v[206:209], v154 offset:16384
	ds_read_b128 v[210:213], v154 offset:18432
	ds_read_b128 v[214:217], v154 offset:20480
	ds_read_b128 v[218:221], v154 offset:22528
	ds_read_b128 v[186:189], v150 offset:2048
	ds_read_b128 v[190:193], v150 offset:4096
	ds_read_b128 v[194:197], v150 offset:6144
	ds_read_b128 v[198:201], v150 offset:8192
	ds_read_b128 v[202:205], v150 offset:10240
	s_add_u32 m0, s101, 0x6000
	s_nop 0
	global_load_lds_dwordx4 v[96:97], off
	v_lshl_add_u64 v[96:97], v[96:97], 0, s[2:3]
	s_add_u32 m0, s101, 0x7000
	s_nop 0
	global_load_lds_dwordx4 v[98:99], off
	v_lshl_add_u64 v[98:99], v[98:99], 0, s[2:3]
	s_add_u32 m0, s101, 0x8000
	s_nop 0
	global_load_lds_dwordx4 v[100:101], off
	v_lshl_add_u64 v[100:101], v[100:101], 0, s[2:3]
	s_add_u32 m0, s101, 0x9000
	s_nop 0
	global_load_lds_dwordx4 v[102:103], off
	v_lshl_add_u64 v[102:103], v[102:103], 0, s[2:3]
	s_add_u32 m0, s101, 0xa000
	s_nop 0
	global_load_lds_dwordx4 v[104:105], off
	v_lshl_add_u64 v[104:105], v[104:105], 0, s[2:3]
	s_mov_b32 s100, 7
.Lgu2_loop:
	s_waitcnt lgkmcnt(8)
	v_mfma_f32_16x16x32_bf16 v[0:3], v[182:185], v[206:209], v[0:3]
	s_add_u32 m0, s101, 0xb000
	ds_read_b128 v[222:225], v153 offset:0
	global_load_lds_dwordx4 v[106:107], off
	v_lshl_add_u64 v[106:107], v[106:107], 0, s[2:3]
	s_waitcnt lgkmcnt(8)
	v_mfma_f32_16x16x32_bf16 v[4:7], v[182:185], v[210:213], v[4:7]
	s_add_u32 m0, s101, 0x10000
	ds_read_b128 v[140:143], v155 offset:16384
	global_load_lds_dwordx4 v[108:109], off
	v_lshl_add_u64 v[108:109], v[108:109], 0, s[2:3]
	s_waitcnt lgkmcnt(8)
	v_mfma_f32_16x16x32_bf16 v[8:11], v[182:185], v[214:217], v[8:11]
	s_add_u32 m0, s101, 0x11000
	ds_read_b128 v[144:147], v155 offset:18432
	global_load_lds_dwordx4 v[110:111], off
	v_lshl_add_u64 v[110:111], v[110:111], 0, s[2:3]
	s_waitcnt lgkmcnt(8)
	v_mfma_f32_16x16x32_bf16 v[12:15], v[182:185], v[218:221], v[12:15]
	s_add_u32 m0, s101, 0x12000
	ds_read_b128 v[116:119], v155 offset:20480
	global_load_lds_dwordx4 v[112:113], off
	v_lshl_add_u64 v[112:113], v[112:113], 0, s[2:3]
	s_waitcnt lgkmcnt(8)
	v_mfma_f32_16x16x32_bf16 v[16:19], v[186:189], v[206:209], v[16:19]
	s_add_u32 m0, s101, 0x13000
	ds_read_b128 v[120:123], v155 offset:22528
	global_load_lds_dwordx4 v[114:115], off
	v_lshl_add_u64 v[114:115], v[114:115], 0, s[2:3]
	v_mfma_f32_16x16x32_bf16 v[20:23], v[186:189], v[210:213], v[20:23]
	ds_read_b128 v[226:229], v153 offset:2048
	v_mfma_f32_16x16x32_bf16 v[24:27], v[186:189], v[214:217], v[24:27]
	ds_read_b128 v[230:233], v153 offset:4096
	v_mfma_f32_16x16x32_bf16 v[28:31], v[186:189], v[218:221], v[28:31]
	ds_read_b128 v[234:237], v153 offset:6144
	s_waitcnt lgkmcnt(11)
	v_mfma_f32_16x16x32_bf16 v[32:35], v[190:193], v[206:209], v[32:35]
	ds_read_b128 v[132:135], v153 offset:8192
	v_mfma_f32_16x16x32_bf16 v[36:39], v[190:193], v[210:213], v[36:39]
	ds_read_b128 v[136:139], v153 offset:10240
	v_mfma_f32_16x16x32_bf16 v[40:43], v[190:193], v[214:217], v[40:43]
	v_mfma_f32_16x16x32_bf16 v[44:47], v[190:193], v[218:221], v[44:47]
	s_waitcnt lgkmcnt(12)
	v_mfma_f32_16x16x32_bf16 v[48:51], v[194:197], v[206:209], v[48:51]
	v_mfma_f32_16x16x32_bf16 v[52:55], v[194:197], v[210:213], v[52:55]
	v_mfma_f32_16x16x32_bf16 v[56:59], v[194:197], v[214:217], v[56:59]
	v_mfma_f32_16x16x32_bf16 v[60:63], v[194:197], v[218:221], v[60:63]
	s_waitcnt lgkmcnt(11)
	v_mfma_f32_16x16x32_bf16 v[64:67], v[198:201], v[206:209], v[64:67]
	v_mfma_f32_16x16x32_bf16 v[68:71], v[198:201], v[210:213], v[68:71]
	v_mfma_f32_16x16x32_bf16 v[72:75], v[198:201], v[214:217], v[72:75]
	v_mfma_f32_16x16x32_bf16 v[76:79], v[198:201], v[218:221], v[76:79]
	s_waitcnt lgkmcnt(10)
	v_mfma_f32_16x16x32_bf16 v[80:83], v[202:205], v[206:209], v[80:83]
	v_mfma_f32_16x16x32_bf16 v[84:87], v[202:205], v[210:213], v[84:87]
	v_mfma_f32_16x16x32_bf16 v[88:91], v[202:205], v[214:217], v[88:91]
	v_mfma_f32_16x16x32_bf16 v[92:95], v[202:205], v[218:221], v[92:95]
	s_waitcnt vmcnt(0) lgkmcnt(0)
	s_barrier
	v_mfma_f32_16x16x32_bf16 v[0:3], v[222:225], v[140:143], v[0:3]
	s_add_u32 m0, s101, 0x0
	ds_read_b128 v[182:185], v150 offset:24576
	global_load_lds_dwordx4 v[96:97], off
	v_lshl_add_u64 v[96:97], v[96:97], 0, s[2:3]
	v_mfma_f32_16x16x32_bf16 v[4:7], v[222:225], v[144:147], v[4:7]
	s_add_u32 m0, s101, 0x1000
	ds_read_b128 v[206:209], v154 offset:32768
	global_load_lds_dwordx4 v[98:99], off
	v_lshl_add_u64 v[98:99], v[98:99], 0, s[2:3]
	v_mfma_f32_16x16x32_bf16 v[8:11], v[222:225], v[116:119], v[8:11]
	s_add_u32 m0, s101, 0x2000
	ds_read_b128 v[210:213], v154 offset:34816
	global_load_lds_dwordx4 v[100:101], off
	v_lshl_add_u64 v[100:101], v[100:101], 0, s[2:3]
	v_mfma_f32_16x16x32_bf16 v[12:15], v[222:225], v[120:123], v[12:15]
	s_add_u32 m0, s101, 0x3000
	ds_read_b128 v[214:217], v154 offset:36864
	global_load_lds_dwordx4 v[102:103], off
	v_lshl_add_u64 v[102:103], v[102:103], 0, s[2:3]
	v_mfma_f32_16x16x32_bf16 v[16:19], v[226:229], v[140:143], v[16:19]
	s_add_u32 m0, s101, 0x4000
	ds_read_b128 v[218:221], v154 offset:38912
	global_load_lds_dwordx4 v[104:105], off
	v_lshl_add_u64 v[104:105], v[104:105], 0, s[2:3]
	v_mfma_f32_16x16x32_bf16 v[20:23], v[226:229], v[144:147], v[20:23]
	ds_read_b128 v[186:189], v150 offset:26624
	v_mfma_f32_16x16x32_bf16 v[24:27], v[226:229], v[116:119], v[24:27]
	ds_read_b128 v[190:193], v150 offset:28672
	v_mfma_f32_16x16x32_bf16 v[28:31], v[226:229], v[120:123], v[28:31]
	ds_read_b128 v[194:197], v150 offset:30720
	v_mfma_f32_16x16x32_bf16 v[32:35], v[230:233], v[140:143], v[32:35]
	ds_read_b128 v[198:201], v150 offset:32768
	v_mfma_f32_16x16x32_bf16 v[36:39], v[230:233], v[144:147], v[36:39]
	ds_read_b128 v[202:205], v150 offset:34816
	v_mfma_f32_16x16x32_bf16 v[40:43], v[230:233], v[116:119], v[40:43]
	v_mfma_f32_16x16x32_bf16 v[44:47], v[230:233], v[120:123], v[44:47]
	v_mfma_f32_16x16x32_bf16 v[48:51], v[234:237], v[140:143], v[48:51]
	v_mfma_f32_16x16x32_bf16 v[52:55], v[234:237], v[144:147], v[52:55]
	v_mfma_f32_16x16x32_bf16 v[56:59], v[234:237], v[116:119], v[56:59]
	v_mfma_f32_16x16x32_bf16 v[60:63], v[234:237], v[120:123], v[60:63]
	v_mfma_f32_16x16x32_bf16 v[64:67], v[132:135], v[140:143], v[64:67]
	v_mfma_f32_16x16x32_bf16 v[68:71], v[132:135], v[144:147], v[68:71]
	v_mfma_f32_16x16x32_bf16 v[72:75], v[132:135], v[116:119], v[72:75]
	v_mfma_f32_16x16x32_bf16 v[76:79], v[132:135], v[120:123], v[76:79]
	v_mfma_f32_16x16x32_bf16 v[80:83], v[136:139], v[140:143], v[80:83]
	v_mfma_f32_16x16x32_bf16 v[84:87], v[136:139], v[144:147], v[84:87]
	v_mfma_f32_16x16x32_bf16 v[88:91], v[136:139], v[116:119], v[88:91]
	v_mfma_f32_16x16x32_bf16 v[92:95], v[136:139], v[120:123], v[92:95]
	s_waitcnt lgkmcnt(8)
	v_mfma_f32_16x16x32_bf16 v[0:3], v[182:185], v[206:209], v[0:3]
	s_add_u32 m0, s101, 0x5000
	ds_read_b128 v[222:225], v153 offset:24576
	global_load_lds_dwordx4 v[106:107], off
	v_lshl_add_u64 v[106:107], v[106:107], 0, s[2:3]
	s_waitcnt lgkmcnt(8)
	v_mfma_f32_16x16x32_bf16 v[4:7], v[182:185], v[210:213], v[4:7]
	s_add_u32 m0, s101, 0xc000
	ds_read_b128 v[140:143], v155 offset:32768
	global_load_lds_dwordx4 v[108:109], off
	v_lshl_add_u64 v[108:109], v[108:109], 0, s[2:3]
	s_waitcnt lgkmcnt(8)
	v_mfma_f32_16x16x32_bf16 v[8:11], v[182:185], v[214:217], v[8:11]
	s_add_u32 m0, s101, 0xd000
	ds_read_b128 v[144:147], v155 offset:34816
	global_load_lds_dwordx4 v[110:111], off
	v_lshl_add_u64 v[110:111], v[110:111], 0, s[2:3]
	s_waitcnt lgkmcnt(8)
	v_mfma_f32_16x16x32_bf16 v[12:15], v[182:185], v[218:221], v[12:15]
	s_add_u32 m0, s101, 0xe000
	ds_read_b128 v[116:119], v155 offset:36864
	global_load_lds_dwordx4 v[112:113], off
	v_lshl_add_u64 v[112:113], v[112:113], 0, s[2:3]
	s_waitcnt lgkmcnt(8)
	v_mfma_f32_16x16x32_bf16 v[16:19], v[186:189], v[206:209], v[16:19]
	s_add_u32 m0, s101, 0xf000
	ds_read_b128 v[120:123], v155 offset:38912
	global_load_lds_dwordx4 v[114:115], off
	v_lshl_add_u64 v[114:115], v[114:115], 0, s[2:3]
	v_mfma_f32_16x16x32_bf16 v[20:23], v[186:189], v[210:213], v[20:23]
	ds_read_b128 v[226:229], v153 offset:26624
	v_mfma_f32_16x16x32_bf16 v[24:27], v[186:189], v[214:217], v[24:27]
	ds_read_b128 v[230:233], v153 offset:28672
	v_mfma_f32_16x16x32_bf16 v[28:31], v[186:189], v[218:221], v[28:31]
	ds_read_b128 v[234:237], v153 offset:30720
	s_waitcnt lgkmcnt(11)
	v_mfma_f32_16x16x32_bf16 v[32:35], v[190:193], v[206:209], v[32:35]
	ds_read_b128 v[132:135], v153 offset:32768
	v_mfma_f32_16x16x32_bf16 v[36:39], v[190:193], v[210:213], v[36:39]
	ds_read_b128 v[136:139], v153 offset:34816
	v_mfma_f32_16x16x32_bf16 v[40:43], v[190:193], v[214:217], v[40:43]
	v_mfma_f32_16x16x32_bf16 v[44:47], v[190:193], v[218:221], v[44:47]
	s_waitcnt lgkmcnt(12)
	v_mfma_f32_16x16x32_bf16 v[48:51], v[194:197], v[206:209], v[48:51]
	v_mfma_f32_16x16x32_bf16 v[52:55], v[194:197], v[210:213], v[52:55]
	v_mfma_f32_16x16x32_bf16 v[56:59], v[194:197], v[214:217], v[56:59]
	v_mfma_f32_16x16x32_bf16 v[60:63], v[194:197], v[218:221], v[60:63]
	s_waitcnt lgkmcnt(11)
	v_mfma_f32_16x16x32_bf16 v[64:67], v[198:201], v[206:209], v[64:67]
	v_mfma_f32_16x16x32_bf16 v[68:71], v[198:201], v[210:213], v[68:71]
	v_mfma_f32_16x16x32_bf16 v[72:75], v[198:201], v[214:217], v[72:75]
	v_mfma_f32_16x16x32_bf16 v[76:79], v[198:201], v[218:221], v[76:79]
	s_waitcnt lgkmcnt(10)
	v_mfma_f32_16x16x32_bf16 v[80:83], v[202:205], v[206:209], v[80:83]
	v_mfma_f32_16x16x32_bf16 v[84:87], v[202:205], v[210:213], v[84:87]
	v_mfma_f32_16x16x32_bf16 v[88:91], v[202:205], v[214:217], v[88:91]
	v_mfma_f32_16x16x32_bf16 v[92:95], v[202:205], v[218:221], v[92:95]
	s_waitcnt vmcnt(0) lgkmcnt(0)
	s_barrier
	v_mfma_f32_16x16x32_bf16 v[0:3], v[222:225], v[140:143], v[0:3]
	s_add_u32 m0, s101, 0x6000
	ds_read_b128 v[182:185], v150 offset:0
	global_load_lds_dwordx4 v[96:97], off
	v_lshl_add_u64 v[96:97], v[96:97], 0, s[2:3]
	v_mfma_f32_16x16x32_bf16 v[4:7], v[222:225], v[144:147], v[4:7]
	s_add_u32 m0, s101, 0x7000
	ds_read_b128 v[206:209], v154 offset:16384
	global_load_lds_dwordx4 v[98:99], off
	v_lshl_add_u64 v[98:99], v[98:99], 0, s[2:3]
	v_mfma_f32_16x16x32_bf16 v[8:11], v[222:225], v[116:119], v[8:11]
	s_add_u32 m0, s101, 0x8000
	ds_read_b128 v[210:213], v154 offset:18432
	global_load_lds_dwordx4 v[100:101], off
	v_lshl_add_u64 v[100:101], v[100:101], 0, s[2:3]
	v_mfma_f32_16x16x32_bf16 v[12:15], v[222:225], v[120:123], v[12:15]
	s_add_u32 m0, s101, 0x9000
	ds_read_b128 v[214:217], v154 offset:20480
	global_load_lds_dwordx4 v[102:103], off
	v_lshl_add_u64 v[102:103], v[102:103], 0, s[2:3]
	v_mfma_f32_16x16x32_bf16 v[16:19], v[226:229], v[140:143], v[16:19]
	s_add_u32 m0, s101, 0xa000
	ds_read_b128 v[218:221], v154 offset:22528
	global_load_lds_dwordx4 v[104:105], off
	v_lshl_add_u64 v[104:105], v[104:105], 0, s[2:3]
	v_mfma_f32_16x16x32_bf16 v[20:23], v[226:229], v[144:147], v[20:23]
	ds_read_b128 v[186:189], v150 offset:2048
	v_mfma_f32_16x16x32_bf16 v[24:27], v[226:229], v[116:119], v[24:27]
	ds_read_b128 v[190:193], v150 offset:4096
	v_mfma_f32_16x16x32_bf16 v[28:31], v[226:229], v[120:123], v[28:31]
	ds_read_b128 v[194:197], v150 offset:6144
	v_mfma_f32_16x16x32_bf16 v[32:35], v[230:233], v[140:143], v[32:35]
	ds_read_b128 v[198:201], v150 offset:8192
	v_mfma_f32_16x16x32_bf16 v[36:39], v[230:233], v[144:147], v[36:39]
	ds_read_b128 v[202:205], v150 offset:10240
	v_mfma_f32_16x16x32_bf16 v[40:43], v[230:233], v[116:119], v[40:43]
	v_mfma_f32_16x16x32_bf16 v[44:47], v[230:233], v[120:123], v[44:47]
	v_mfma_f32_16x16x32_bf16 v[48:51], v[234:237], v[140:143], v[48:51]
	v_mfma_f32_16x16x32_bf16 v[52:55], v[234:237], v[144:147], v[52:55]
	v_mfma_f32_16x16x32_bf16 v[56:59], v[234:237], v[116:119], v[56:59]
	v_mfma_f32_16x16x32_bf16 v[60:63], v[234:237], v[120:123], v[60:63]
	v_mfma_f32_16x16x32_bf16 v[64:67], v[132:135], v[140:143], v[64:67]
	v_mfma_f32_16x16x32_bf16 v[68:71], v[132:135], v[144:147], v[68:71]
	v_mfma_f32_16x16x32_bf16 v[72:75], v[132:135], v[116:119], v[72:75]
	v_mfma_f32_16x16x32_bf16 v[76:79], v[132:135], v[120:123], v[76:79]
	v_mfma_f32_16x16x32_bf16 v[80:83], v[136:139], v[140:143], v[80:83]
	v_mfma_f32_16x16x32_bf16 v[84:87], v[136:139], v[144:147], v[84:87]
	v_mfma_f32_16x16x32_bf16 v[88:91], v[136:139], v[116:119], v[88:91]
	v_mfma_f32_16x16x32_bf16 v[92:95], v[136:139], v[120:123], v[92:95]
	s_add_i32 s100, s100, -1
	s_cmp_lg_u32 s100, 0
	s_cbranch_scc1 .Lgu2_loop
	s_waitcnt lgkmcnt(8)
	v_mfma_f32_16x16x32_bf16 v[0:3], v[182:185], v[206:209], v[0:3]
	s_add_u32 m0, s101, 0xb000
	ds_read_b128 v[222:225], v153 offset:0
	global_load_lds_dwordx4 v[106:107], off
	v_lshl_add_u64 v[106:107], v[106:107], 0, s[2:3]
	s_waitcnt lgkmcnt(8)
	v_mfma_f32_16x16x32_bf16 v[4:7], v[182:185], v[210:213], v[4:7]
	s_add_u32 m0, s101, 0x10000
	ds_read_b128 v[140:143], v155 offset:16384
	global_load_lds_dwordx4 v[108:109], off
	v_lshl_add_u64 v[108:109], v[108:109], 0, s[2:3]
	s_waitcnt lgkmcnt(8)
	v_mfma_f32_16x16x32_bf16 v[8:11], v[182:185], v[214:217], v[8:11]
	s_add_u32 m0, s101, 0x11000
	ds_read_b128 v[144:147], v155 offset:18432
	global_load_lds_dwordx4 v[110:111], off
	v_lshl_add_u64 v[110:111], v[110:111], 0, s[2:3]
	s_waitcnt lgkmcnt(8)
	v_mfma_f32_16x16x32_bf16 v[12:15], v[182:185], v[218:221], v[12:15]
	s_add_u32 m0, s101, 0x12000
	ds_read_b128 v[116:119], v155 offset:20480
	global_load_lds_dwordx4 v[112:113], off
	v_lshl_add_u64 v[112:113], v[112:113], 0, s[2:3]
	s_waitcnt lgkmcnt(8)
	v_mfma_f32_16x16x32_bf16 v[16:19], v[186:189], v[206:209], v[16:19]
	s_add_u32 m0, s101, 0x13000
	ds_read_b128 v[120:123], v155 offset:22528
	global_load_lds_dwordx4 v[114:115], off
	v_lshl_add_u64 v[114:115], v[114:115], 0, s[2:3]
	v_mfma_f32_16x16x32_bf16 v[20:23], v[186:189], v[210:213], v[20:23]
	ds_read_b128 v[226:229], v153 offset:2048
	v_mfma_f32_16x16x32_bf16 v[24:27], v[186:189], v[214:217], v[24:27]
	ds_read_b128 v[230:233], v153 offset:4096
	v_mfma_f32_16x16x32_bf16 v[28:31], v[186:189], v[218:221], v[28:31]
	ds_read_b128 v[234:237], v153 offset:6144
	s_waitcnt lgkmcnt(11)
	v_mfma_f32_16x16x32_bf16 v[32:35], v[190:193], v[206:209], v[32:35]
	ds_read_b128 v[132:135], v153 offset:8192
	v_mfma_f32_16x16x32_bf16 v[36:39], v[190:193], v[210:213], v[36:39]
	ds_read_b128 v[136:139], v153 offset:10240
	v_mfma_f32_16x16x32_bf16 v[40:43], v[190:193], v[214:217], v[40:43]
	v_mfma_f32_16x16x32_bf16 v[44:47], v[190:193], v[218:221], v[44:47]
	s_waitcnt lgkmcnt(12)
	v_mfma_f32_16x16x32_bf16 v[48:51], v[194:197], v[206:209], v[48:51]
	v_mfma_f32_16x16x32_bf16 v[52:55], v[194:197], v[210:213], v[52:55]
	v_mfma_f32_16x16x32_bf16 v[56:59], v[194:197], v[214:217], v[56:59]
	v_mfma_f32_16x16x32_bf16 v[60:63], v[194:197], v[218:221], v[60:63]
	s_waitcnt lgkmcnt(11)
	v_mfma_f32_16x16x32_bf16 v[64:67], v[198:201], v[206:209], v[64:67]
	v_mfma_f32_16x16x32_bf16 v[68:71], v[198:201], v[210:213], v[68:71]
	v_mfma_f32_16x16x32_bf16 v[72:75], v[198:201], v[214:217], v[72:75]
	v_mfma_f32_16x16x32_bf16 v[76:79], v[198:201], v[218:221], v[76:79]
	s_waitcnt lgkmcnt(10)
	v_mfma_f32_16x16x32_bf16 v[80:83], v[202:205], v[206:209], v[80:83]
	v_mfma_f32_16x16x32_bf16 v[84:87], v[202:205], v[210:213], v[84:87]
	v_mfma_f32_16x16x32_bf16 v[88:91], v[202:205], v[214:217], v[88:91]
	v_mfma_f32_16x16x32_bf16 v[92:95], v[202:205], v[218:221], v[92:95]
	s_waitcnt vmcnt(0) lgkmcnt(0)
	s_barrier
	v_mfma_f32_16x16x32_bf16 v[0:3], v[222:225], v[140:143], v[0:3]
	ds_read_b128 v[182:185], v150 offset:24576
	v_mfma_f32_16x16x32_bf16 v[4:7], v[222:225], v[144:147], v[4:7]
	ds_read_b128 v[206:209], v154 offset:32768
	v_mfma_f32_16x16x32_bf16 v[8:11], v[222:225], v[116:119], v[8:11]
	ds_read_b128 v[210:213], v154 offset:34816
	v_mfma_f32_16x16x32_bf16 v[12:15], v[222:225], v[120:123], v[12:15]
	ds_read_b128 v[214:217], v154 offset:36864
	v_mfma_f32_16x16x32_bf16 v[16:19], v[226:229], v[140:143], v[16:19]
	ds_read_b128 v[218:221], v154 offset:38912
	v_mfma_f32_16x16x32_bf16 v[20:23], v[226:229], v[144:147], v[20:23]
	ds_read_b128 v[186:189], v150 offset:26624
	v_mfma_f32_16x16x32_bf16 v[24:27], v[226:229], v[116:119], v[24:27]
	ds_read_b128 v[190:193], v150 offset:28672
	v_mfma_f32_16x16x32_bf16 v[28:31], v[226:229], v[120:123], v[28:31]
	ds_read_b128 v[194:197], v150 offset:30720
	v_mfma_f32_16x16x32_bf16 v[32:35], v[230:233], v[140:143], v[32:35]
	ds_read_b128 v[198:201], v150 offset:32768
	v_mfma_f32_16x16x32_bf16 v[36:39], v[230:233], v[144:147], v[36:39]
	ds_read_b128 v[202:205], v150 offset:34816
	v_mfma_f32_16x16x32_bf16 v[40:43], v[230:233], v[116:119], v[40:43]
	v_mfma_f32_16x16x32_bf16 v[44:47], v[230:233], v[120:123], v[44:47]
	v_mfma_f32_16x16x32_bf16 v[48:51], v[234:237], v[140:143], v[48:51]
	v_mfma_f32_16x16x32_bf16 v[52:55], v[234:237], v[144:147], v[52:55]
	v_mfma_f32_16x16x32_bf16 v[56:59], v[234:237], v[116:119], v[56:59]
	v_mfma_f32_16x16x32_bf16 v[60:63], v[234:237], v[120:123], v[60:63]
	v_mfma_f32_16x16x32_bf16 v[64:67], v[132:135], v[140:143], v[64:67]
	v_mfma_f32_16x16x32_bf16 v[68:71], v[132:135], v[144:147], v[68:71]
	v_mfma_f32_16x16x32_bf16 v[72:75], v[132:135], v[116:119], v[72:75]
	v_mfma_f32_16x16x32_bf16 v[76:79], v[132:135], v[120:123], v[76:79]
	v_mfma_f32_16x16x32_bf16 v[80:83], v[136:139], v[140:143], v[80:83]
	v_mfma_f32_16x16x32_bf16 v[84:87], v[136:139], v[144:147], v[84:87]
	v_mfma_f32_16x16x32_bf16 v[88:91], v[136:139], v[116:119], v[88:91]
	v_mfma_f32_16x16x32_bf16 v[92:95], v[136:139], v[120:123], v[92:95]
	s_waitcnt lgkmcnt(8)
	v_mfma_f32_16x16x32_bf16 v[0:3], v[182:185], v[206:209], v[0:3]
	ds_read_b128 v[222:225], v153 offset:24576
	s_waitcnt lgkmcnt(8)
	v_mfma_f32_16x16x32_bf16 v[4:7], v[182:185], v[210:213], v[4:7]
	ds_read_b128 v[140:143], v155 offset:32768
	s_waitcnt lgkmcnt(8)
	v_mfma_f32_16x16x32_bf16 v[8:11], v[182:185], v[214:217], v[8:11]
	ds_read_b128 v[144:147], v155 offset:34816
	s_waitcnt lgkmcnt(8)
	v_mfma_f32_16x16x32_bf16 v[12:15], v[182:185], v[218:221], v[12:15]
	ds_read_b128 v[116:119], v155 offset:36864
	s_waitcnt lgkmcnt(8)
	v_mfma_f32_16x16x32_bf16 v[16:19], v[186:189], v[206:209], v[16:19]
	ds_read_b128 v[120:123], v155 offset:38912
	v_mfma_f32_16x16x32_bf16 v[20:23], v[186:189], v[210:213], v[20:23]
	ds_read_b128 v[226:229], v153 offset:26624
	v_mfma_f32_16x16x32_bf16 v[24:27], v[186:189], v[214:217], v[24:27]
	ds_read_b128 v[230:233], v153 offset:28672
	v_mfma_f32_16x16x32_bf16 v[28:31], v[186:189], v[218:221], v[28:31]
	ds_read_b128 v[234:237], v153 offset:30720
	s_waitcnt lgkmcnt(11)
	v_mfma_f32_16x16x32_bf16 v[32:35], v[190:193], v[206:209], v[32:35]
	ds_read_b128 v[132:135], v153 offset:32768
	v_mfma_f32_16x16x32_bf16 v[36:39], v[190:193], v[210:213], v[36:39]
	ds_read_b128 v[136:139], v153 offset:34816
	v_mfma_f32_16x16x32_bf16 v[40:43], v[190:193], v[214:217], v[40:43]
	v_mfma_f32_16x16x32_bf16 v[44:47], v[190:193], v[218:221], v[44:47]
	s_waitcnt lgkmcnt(12)
	v_mfma_f32_16x16x32_bf16 v[48:51], v[194:197], v[206:209], v[48:51]
	v_mfma_f32_16x16x32_bf16 v[52:55], v[194:197], v[210:213], v[52:55]
	v_mfma_f32_16x16x32_bf16 v[56:59], v[194:197], v[214:217], v[56:59]
	v_mfma_f32_16x16x32_bf16 v[60:63], v[194:197], v[218:221], v[60:63]
	s_waitcnt lgkmcnt(11)
	v_mfma_f32_16x16x32_bf16 v[64:67], v[198:201], v[206:209], v[64:67]
	v_mfma_f32_16x16x32_bf16 v[68:71], v[198:201], v[210:213], v[68:71]
	v_mfma_f32_16x16x32_bf16 v[72:75], v[198:201], v[214:217], v[72:75]
	v_mfma_f32_16x16x32_bf16 v[76:79], v[198:201], v[218:221], v[76:79]
	s_waitcnt lgkmcnt(10)
	v_mfma_f32_16x16x32_bf16 v[80:83], v[202:205], v[206:209], v[80:83]
	v_mfma_f32_16x16x32_bf16 v[84:87], v[202:205], v[210:213], v[84:87]
	v_mfma_f32_16x16x32_bf16 v[88:91], v[202:205], v[214:217], v[88:91]
	v_mfma_f32_16x16x32_bf16 v[92:95], v[202:205], v[218:221], v[92:95]
	s_waitcnt vmcnt(0) lgkmcnt(0)
	s_barrier
	v_mfma_f32_16x16x32_bf16 v[0:3], v[222:225], v[140:143], v[0:3]
	v_mfma_f32_16x16x32_bf16 v[4:7], v[222:225], v[144:147], v[4:7]
	v_mfma_f32_16x16x32_bf16 v[8:11], v[222:225], v[116:119], v[8:11]
	v_mfma_f32_16x16x32_bf16 v[12:15], v[222:225], v[120:123], v[12:15]
	v_mfma_f32_16x16x32_bf16 v[16:19], v[226:229], v[140:143], v[16:19]
	v_mfma_f32_16x16x32_bf16 v[20:23], v[226:229], v[144:147], v[20:23]
	v_mfma_f32_16x16x32_bf16 v[24:27], v[226:229], v[116:119], v[24:27]
	v_mfma_f32_16x16x32_bf16 v[28:31], v[226:229], v[120:123], v[28:31]
	v_mfma_f32_16x16x32_bf16 v[32:35], v[230:233], v[140:143], v[32:35]
	v_mfma_f32_16x16x32_bf16 v[36:39], v[230:233], v[144:147], v[36:39]
	v_mfma_f32_16x16x32_bf16 v[40:43], v[230:233], v[116:119], v[40:43]
	v_mfma_f32_16x16x32_bf16 v[44:47], v[230:233], v[120:123], v[44:47]
	v_mfma_f32_16x16x32_bf16 v[48:51], v[234:237], v[140:143], v[48:51]
	v_mfma_f32_16x16x32_bf16 v[52:55], v[234:237], v[144:147], v[52:55]
	v_mfma_f32_16x16x32_bf16 v[56:59], v[234:237], v[116:119], v[56:59]
	v_mfma_f32_16x16x32_bf16 v[60:63], v[234:237], v[120:123], v[60:63]
	v_mfma_f32_16x16x32_bf16 v[64:67], v[132:135], v[140:143], v[64:67]
	v_mfma_f32_16x16x32_bf16 v[68:71], v[132:135], v[144:147], v[68:71]
	v_mfma_f32_16x16x32_bf16 v[72:75], v[132:135], v[116:119], v[72:75]
	v_mfma_f32_16x16x32_bf16 v[76:79], v[132:135], v[120:123], v[76:79]
	v_mfma_f32_16x16x32_bf16 v[80:83], v[136:139], v[140:143], v[80:83]
	v_mfma_f32_16x16x32_bf16 v[84:87], v[136:139], v[144:147], v[84:87]
	v_mfma_f32_16x16x32_bf16 v[88:91], v[136:139], v[116:119], v[88:91]
	v_mfma_f32_16x16x32_bf16 v[92:95], v[136:139], v[120:123], v[92:95]
	s_nop 7
	s_nop 7
	s_branch .LBB0_82

.LBB0_1335:
	s_nop 2
	v_and_b32_e32 v99, 15, v129
	v_lshl_or_b32 v96, s18, 6, v99
	v_lshl_add_u32 v96, v151, 5, v96
	v_bfe_u32 v97, v129, 4, 2
	v_lshlrev_b32_e32 v97, 2, v97
	s_movk_i32 s14, 0x1600
	v_add3_u32 v97, v97, v152, s17
	v_mul_lo_u32 v98, v97, s14
	v_lshl_add_u32 v98, v96, 1, v98
	v_mul_f32_e32 v100, 0xbfb8aa3b, v0
	v_mul_f32_e32 v101, 0xbfb8aa3b, v1
	v_mul_f32_e32 v102, 0xbfb8aa3b, v2
	v_mul_f32_e32 v103, 0xbfb8aa3b, v3
	v_exp_f32_e32 v100, v100
	v_exp_f32_e32 v101, v101
	v_exp_f32_e32 v102, v102
	v_exp_f32_e32 v103, v103
	v_mov_b32_e32 v104, v98
	v_add_u32_e32 v105, 0x1600, v98
	v_add_u32_e32 v106, 0x2c00, v98
	v_add_u32_e32 v107, 0x4200, v98
	v_add_f32_e32 v100, 1.0, v100
	v_add_f32_e32 v101, 1.0, v101
	v_add_f32_e32 v102, 1.0, v102
	v_add_f32_e32 v103, 1.0, v103
	v_rcp_f32_e32 v100, v100
	v_rcp_f32_e32 v101, v101
	v_rcp_f32_e32 v102, v102
	v_rcp_f32_e32 v103, v103
	s_nop 0
	v_mul_f32_e32 v0, v0, v100
	v_mul_f32_e32 v1, v1, v101
	v_mul_f32_e32 v2, v2, v102
	v_mul_f32_e32 v3, v3, v103
	v_mul_f32_e32 v0, v8, v0
	v_mul_f32_e32 v1, v9, v1
	v_mul_f32_e32 v2, v10, v2
	v_mul_f32_e32 v3, v11, v3
	v_bfe_u32 v100, v0, 16, 1
	v_bfe_u32 v101, v1, 16, 1
	v_bfe_u32 v102, v2, 16, 1
	v_bfe_u32 v103, v3, 16, 1
	v_add3_u32 v0, v0, v100, s33
	v_add3_u32 v1, v1, v101, s33
	v_add3_u32 v2, v2, v102, s33
	v_add3_u32 v3, v3, v103, s33
	global_store_short_d16_hi v104, v0, s[4:5]
	global_store_short_d16_hi v105, v1, s[4:5]
	global_store_short_d16_hi v106, v2, s[4:5]
	global_store_short_d16_hi v107, v3, s[4:5]
	v_mul_f32_e32 v100, 0xbfb8aa3b, v4
	v_mul_f32_e32 v101, 0xbfb8aa3b, v5
	v_mul_f32_e32 v102, 0xbfb8aa3b, v6
	v_mul_f32_e32 v103, 0xbfb8aa3b, v7
	v_exp_f32_e32 v100, v100
	v_exp_f32_e32 v101, v101
	v_exp_f32_e32 v102, v102
	v_exp_f32_e32 v103, v103
	v_add_u32_e32 v104, 0x20, v98
	v_add_u32_e32 v105, 0x1620, v98
	v_add_u32_e32 v106, 0x2c20, v98
	v_add_u32_e32 v107, 0x4220, v98
	v_add_f32_e32 v100, 1.0, v100
	v_add_f32_e32 v101, 1.0, v101
	v_add_f32_e32 v102, 1.0, v102
	v_add_f32_e32 v103, 1.0, v103
	v_rcp_f32_e32 v100, v100
	v_rcp_f32_e32 v101, v101
	v_rcp_f32_e32 v102, v102
	v_rcp_f32_e32 v103, v103
	s_nop 0
	v_mul_f32_e32 v4, v4, v100
	v_mul_f32_e32 v5, v5, v101
	v_mul_f32_e32 v6, v6, v102
	v_mul_f32_e32 v7, v7, v103
	v_mul_f32_e32 v4, v12, v4
	v_mul_f32_e32 v5, v13, v5
	v_mul_f32_e32 v6, v14, v6
	v_mul_f32_e32 v7, v15, v7
	v_bfe_u32 v100, v4, 16, 1
	v_bfe_u32 v101, v5, 16, 1
	v_bfe_u32 v102, v6, 16, 1
	v_bfe_u32 v103, v7, 16, 1
	v_add3_u32 v4, v4, v100, s33
	v_add3_u32 v5, v5, v101, s33
	v_add3_u32 v6, v6, v102, s33
	v_add3_u32 v7, v7, v103, s33
	global_store_short_d16_hi v104, v4, s[4:5]
	global_store_short_d16_hi v105, v5, s[4:5]
	global_store_short_d16_hi v106, v6, s[4:5]
	global_store_short_d16_hi v107, v7, s[4:5]
	v_mul_f32_e32 v100, 0xbfb8aa3b, v16
	v_mul_f32_e32 v101, 0xbfb8aa3b, v17
	v_mul_f32_e32 v102, 0xbfb8aa3b, v18
	v_mul_f32_e32 v103, 0xbfb8aa3b, v19
	v_exp_f32_e32 v100, v100
	v_exp_f32_e32 v101, v101
	v_exp_f32_e32 v102, v102
	v_exp_f32_e32 v103, v103
	v_add_u32_e32 v104, 0x16000, v98
	v_add_u32_e32 v105, 0x17600, v98
	v_add_u32_e32 v106, 0x18c00, v98
	v_add_u32_e32 v107, 0x1a200, v98
	v_add_f32_e32 v100, 1.0, v100
	v_add_f32_e32 v101, 1.0, v101
	v_add_f32_e32 v102, 1.0, v102
	v_add_f32_e32 v103, 1.0, v103
	v_rcp_f32_e32 v100, v100
	v_rcp_f32_e32 v101, v101
	v_rcp_f32_e32 v102, v102
	v_rcp_f32_e32 v103, v103
	s_nop 0
	v_mul_f32_e32 v16, v16, v100
	v_mul_f32_e32 v17, v17, v101
	v_mul_f32_e32 v18, v18, v102
	v_mul_f32_e32 v19, v19, v103
	v_mul_f32_e32 v16, v24, v16
	v_mul_f32_e32 v17, v25, v17
	v_mul_f32_e32 v18, v26, v18
	v_mul_f32_e32 v19, v27, v19
	v_bfe_u32 v100, v16, 16, 1
	v_bfe_u32 v101, v17, 16, 1
	v_bfe_u32 v102, v18, 16, 1
	v_bfe_u32 v103, v19, 16, 1
	v_add3_u32 v16, v16, v100, s33
	v_add3_u32 v17, v17, v101, s33
	v_add3_u32 v18, v18, v102, s33
	v_add3_u32 v19, v19, v103, s33
	global_store_short_d16_hi v104, v16, s[4:5]
	global_store_short_d16_hi v105, v17, s[4:5]
	global_store_short_d16_hi v106, v18, s[4:5]
	global_store_short_d16_hi v107, v19, s[4:5]
	v_mul_f32_e32 v100, 0xbfb8aa3b, v20
	v_mul_f32_e32 v101, 0xbfb8aa3b, v21
	v_mul_f32_e32 v102, 0xbfb8aa3b, v22
	v_mul_f32_e32 v103, 0xbfb8aa3b, v23
	v_exp_f32_e32 v100, v100
	v_exp_f32_e32 v101, v101
	v_exp_f32_e32 v102, v102
	v_exp_f32_e32 v103, v103
	v_add_u32_e32 v104, 0x16020, v98
	v_add_u32_e32 v105, 0x17620, v98
	v_add_u32_e32 v106, 0x18c20, v98
	v_add_u32_e32 v107, 0x1a220, v98
	v_add_f32_e32 v100, 1.0, v100
	v_add_f32_e32 v101, 1.0, v101
	v_add_f32_e32 v102, 1.0, v102
	v_add_f32_e32 v103, 1.0, v103
	v_rcp_f32_e32 v100, v100
	v_rcp_f32_e32 v101, v101
	v_rcp_f32_e32 v102, v102
	v_rcp_f32_e32 v103, v103
	s_nop 0
	v_mul_f32_e32 v20, v20, v100
	v_mul_f32_e32 v21, v21, v101
	v_mul_f32_e32 v22, v22, v102
	v_mul_f32_e32 v23, v23, v103
	v_mul_f32_e32 v20, v28, v20
	v_mul_f32_e32 v21, v29, v21
	v_mul_f32_e32 v22, v30, v22
	v_mul_f32_e32 v23, v31, v23
	v_bfe_u32 v100, v20, 16, 1
	v_bfe_u32 v101, v21, 16, 1
	v_bfe_u32 v102, v22, 16, 1
	v_bfe_u32 v103, v23, 16, 1
	v_add3_u32 v20, v20, v100, s33
	v_add3_u32 v21, v21, v101, s33
	v_add3_u32 v22, v22, v102, s33
	v_add3_u32 v23, v23, v103, s33
	global_store_short_d16_hi v104, v20, s[4:5]
	global_store_short_d16_hi v105, v21, s[4:5]
	global_store_short_d16_hi v106, v22, s[4:5]
	global_store_short_d16_hi v107, v23, s[4:5]
	v_mul_f32_e32 v100, 0xbfb8aa3b, v32
	v_mul_f32_e32 v101, 0xbfb8aa3b, v33
	v_mul_f32_e32 v102, 0xbfb8aa3b, v34
	v_mul_f32_e32 v103, 0xbfb8aa3b, v35
	v_exp_f32_e32 v100, v100
	v_exp_f32_e32 v101, v101
	v_exp_f32_e32 v102, v102
	v_exp_f32_e32 v103, v103
	v_add_u32_e32 v104, 0x2c000, v98
	v_add_u32_e32 v105, 0x2d600, v98
	v_add_u32_e32 v106, 0x2ec00, v98
	v_add_u32_e32 v107, 0x30200, v98
	v_add_f32_e32 v100, 1.0, v100
	v_add_f32_e32 v101, 1.0, v101
	v_add_f32_e32 v102, 1.0, v102
	v_add_f32_e32 v103, 1.0, v103
	v_rcp_f32_e32 v100, v100
	v_rcp_f32_e32 v101, v101
	v_rcp_f32_e32 v102, v102
	v_rcp_f32_e32 v103, v103
	s_nop 0
	v_mul_f32_e32 v32, v32, v100
	v_mul_f32_e32 v33, v33, v101
	v_mul_f32_e32 v34, v34, v102
	v_mul_f32_e32 v35, v35, v103
	v_mul_f32_e32 v32, v40, v32
	v_mul_f32_e32 v33, v41, v33
	v_mul_f32_e32 v34, v42, v34
	v_mul_f32_e32 v35, v43, v35
	v_bfe_u32 v100, v32, 16, 1
	v_bfe_u32 v101, v33, 16, 1
	v_bfe_u32 v102, v34, 16, 1
	v_bfe_u32 v103, v35, 16, 1
	v_add3_u32 v32, v32, v100, s33
	v_add3_u32 v33, v33, v101, s33
	v_add3_u32 v34, v34, v102, s33
	v_add3_u32 v35, v35, v103, s33
	global_store_short_d16_hi v104, v32, s[4:5]
	global_store_short_d16_hi v105, v33, s[4:5]
	global_store_short_d16_hi v106, v34, s[4:5]
	global_store_short_d16_hi v107, v35, s[4:5]
	v_mul_f32_e32 v100, 0xbfb8aa3b, v36
	v_mul_f32_e32 v101, 0xbfb8aa3b, v37
	v_mul_f32_e32 v102, 0xbfb8aa3b, v38
	v_mul_f32_e32 v103, 0xbfb8aa3b, v39
	v_exp_f32_e32 v100, v100
	v_exp_f32_e32 v101, v101
	v_exp_f32_e32 v102, v102
	v_exp_f32_e32 v103, v103
	v_add_u32_e32 v104, 0x2c020, v98
	v_add_u32_e32 v105, 0x2d620, v98
	v_add_u32_e32 v106, 0x2ec20, v98
	v_add_u32_e32 v107, 0x30220, v98
	v_add_f32_e32 v100, 1.0, v100
	v_add_f32_e32 v101, 1.0, v101
	v_add_f32_e32 v102, 1.0, v102
	v_add_f32_e32 v103, 1.0, v103
	v_rcp_f32_e32 v100, v100
	v_rcp_f32_e32 v101, v101
	v_rcp_f32_e32 v102, v102
	v_rcp_f32_e32 v103, v103
	s_nop 0
	v_mul_f32_e32 v36, v36, v100
	v_mul_f32_e32 v37, v37, v101
	v_mul_f32_e32 v38, v38, v102
	v_mul_f32_e32 v39, v39, v103
	v_mul_f32_e32 v36, v44, v36
	v_mul_f32_e32 v37, v45, v37
	v_mul_f32_e32 v38, v46, v38
	v_mul_f32_e32 v39, v47, v39
	v_bfe_u32 v100, v36, 16, 1
	v_bfe_u32 v101, v37, 16, 1
	v_bfe_u32 v102, v38, 16, 1
	v_bfe_u32 v103, v39, 16, 1
	v_add3_u32 v36, v36, v100, s33
	v_add3_u32 v37, v37, v101, s33
	v_add3_u32 v38, v38, v102, s33
	v_add3_u32 v39, v39, v103, s33
	global_store_short_d16_hi v104, v36, s[4:5]
	global_store_short_d16_hi v105, v37, s[4:5]
	global_store_short_d16_hi v106, v38, s[4:5]
	global_store_short_d16_hi v107, v39, s[4:5]
	v_mul_f32_e32 v100, 0xbfb8aa3b, v48
	v_mul_f32_e32 v101, 0xbfb8aa3b, v49
	v_mul_f32_e32 v102, 0xbfb8aa3b, v50
	v_mul_f32_e32 v103, 0xbfb8aa3b, v51
	v_exp_f32_e32 v100, v100
	v_exp_f32_e32 v101, v101
	v_exp_f32_e32 v102, v102
	v_exp_f32_e32 v103, v103
	v_add_u32_e32 v104, 0x42000, v98
	v_add_u32_e32 v105, 0x43600, v98
	v_add_u32_e32 v106, 0x44c00, v98
	v_add_u32_e32 v107, 0x46200, v98
	v_add_f32_e32 v100, 1.0, v100
	v_add_f32_e32 v101, 1.0, v101
	v_add_f32_e32 v102, 1.0, v102
	v_add_f32_e32 v103, 1.0, v103
	v_rcp_f32_e32 v100, v100
	v_rcp_f32_e32 v101, v101
	v_rcp_f32_e32 v102, v102
	v_rcp_f32_e32 v103, v103
	s_nop 0
	v_mul_f32_e32 v48, v48, v100
	v_mul_f32_e32 v49, v49, v101
	v_mul_f32_e32 v50, v50, v102
	v_mul_f32_e32 v51, v51, v103
	v_mul_f32_e32 v48, v56, v48
	v_mul_f32_e32 v49, v57, v49
	v_mul_f32_e32 v50, v58, v50
	v_mul_f32_e32 v51, v59, v51
	v_bfe_u32 v100, v48, 16, 1
	v_bfe_u32 v101, v49, 16, 1
	v_bfe_u32 v102, v50, 16, 1
	v_bfe_u32 v103, v51, 16, 1
	v_add3_u32 v48, v48, v100, s33
	v_add3_u32 v49, v49, v101, s33
	v_add3_u32 v50, v50, v102, s33
	v_add3_u32 v51, v51, v103, s33
	global_store_short_d16_hi v104, v48, s[4:5]
	global_store_short_d16_hi v105, v49, s[4:5]
	global_store_short_d16_hi v106, v50, s[4:5]
	global_store_short_d16_hi v107, v51, s[4:5]
	v_mul_f32_e32 v100, 0xbfb8aa3b, v52
	v_mul_f32_e32 v101, 0xbfb8aa3b, v53
	v_mul_f32_e32 v102, 0xbfb8aa3b, v54
	v_mul_f32_e32 v103, 0xbfb8aa3b, v55
	v_exp_f32_e32 v100, v100
	v_exp_f32_e32 v101, v101
	v_exp_f32_e32 v102, v102
	v_exp_f32_e32 v103, v103
	v_add_u32_e32 v104, 0x42020, v98
	v_add_u32_e32 v105, 0x43620, v98
	v_add_u32_e32 v106, 0x44c20, v98
	v_add_u32_e32 v107, 0x46220, v98
	v_add_f32_e32 v100, 1.0, v100
	v_add_f32_e32 v101, 1.0, v101
	v_add_f32_e32 v102, 1.0, v102
	v_add_f32_e32 v103, 1.0, v103
	v_rcp_f32_e32 v100, v100
	v_rcp_f32_e32 v101, v101
	v_rcp_f32_e32 v102, v102
	v_rcp_f32_e32 v103, v103
	s_nop 0
	v_mul_f32_e32 v52, v52, v100
	v_mul_f32_e32 v53, v53, v101
	v_mul_f32_e32 v54, v54, v102
	v_mul_f32_e32 v55, v55, v103
	v_mul_f32_e32 v52, v60, v52
	v_mul_f32_e32 v53, v61, v53
	v_mul_f32_e32 v54, v62, v54
	v_mul_f32_e32 v55, v63, v55
	v_bfe_u32 v100, v52, 16, 1
	v_bfe_u32 v101, v53, 16, 1
	v_bfe_u32 v102, v54, 16, 1
	v_bfe_u32 v103, v55, 16, 1
	v_add3_u32 v52, v52, v100, s33
	v_add3_u32 v53, v53, v101, s33
	v_add3_u32 v54, v54, v102, s33
	v_add3_u32 v55, v55, v103, s33
	global_store_short_d16_hi v104, v52, s[4:5]
	global_store_short_d16_hi v105, v53, s[4:5]
	global_store_short_d16_hi v106, v54, s[4:5]
	global_store_short_d16_hi v107, v55, s[4:5]
	v_mul_f32_e32 v100, 0xbfb8aa3b, v64
	v_mul_f32_e32 v101, 0xbfb8aa3b, v65
	v_mul_f32_e32 v102, 0xbfb8aa3b, v66
	v_mul_f32_e32 v103, 0xbfb8aa3b, v67
	v_exp_f32_e32 v100, v100
	v_exp_f32_e32 v101, v101
	v_exp_f32_e32 v102, v102
	v_exp_f32_e32 v103, v103
	v_add_u32_e32 v104, 0x58000, v98
	v_add_u32_e32 v105, 0x59600, v98
	v_add_u32_e32 v106, 0x5ac00, v98
	v_add_u32_e32 v107, 0x5c200, v98
	v_add_f32_e32 v100, 1.0, v100
	v_add_f32_e32 v101, 1.0, v101
	v_add_f32_e32 v102, 1.0, v102
	v_add_f32_e32 v103, 1.0, v103
	v_rcp_f32_e32 v100, v100
	v_rcp_f32_e32 v101, v101
	v_rcp_f32_e32 v102, v102
	v_rcp_f32_e32 v103, v103
	s_nop 0
	v_mul_f32_e32 v64, v64, v100
	v_mul_f32_e32 v65, v65, v101
	v_mul_f32_e32 v66, v66, v102
	v_mul_f32_e32 v67, v67, v103
	v_mul_f32_e32 v64, v72, v64
	v_mul_f32_e32 v65, v73, v65
	v_mul_f32_e32 v66, v74, v66
	v_mul_f32_e32 v67, v75, v67
	v_bfe_u32 v100, v64, 16, 1
	v_bfe_u32 v101, v65, 16, 1
	v_bfe_u32 v102, v66, 16, 1
	v_bfe_u32 v103, v67, 16, 1
	v_add3_u32 v64, v64, v100, s33
	v_add3_u32 v65, v65, v101, s33
	v_add3_u32 v66, v66, v102, s33
	v_add3_u32 v67, v67, v103, s33
	global_store_short_d16_hi v104, v64, s[4:5]
	global_store_short_d16_hi v105, v65, s[4:5]
	global_store_short_d16_hi v106, v66, s[4:5]
	global_store_short_d16_hi v107, v67, s[4:5]
	v_mul_f32_e32 v100, 0xbfb8aa3b, v68
	v_mul_f32_e32 v101, 0xbfb8aa3b, v69
	v_mul_f32_e32 v102, 0xbfb8aa3b, v70
	v_mul_f32_e32 v103, 0xbfb8aa3b, v71
	v_exp_f32_e32 v100, v100
	v_exp_f32_e32 v101, v101
	v_exp_f32_e32 v102, v102
	v_exp_f32_e32 v103, v103
	v_add_u32_e32 v104, 0x58020, v98
	v_add_u32_e32 v105, 0x59620, v98
	v_add_u32_e32 v106, 0x5ac20, v98
	v_add_u32_e32 v107, 0x5c220, v98
	v_add_f32_e32 v100, 1.0, v100
	v_add_f32_e32 v101, 1.0, v101
	v_add_f32_e32 v102, 1.0, v102
	v_add_f32_e32 v103, 1.0, v103
	v_rcp_f32_e32 v100, v100
	v_rcp_f32_e32 v101, v101
	v_rcp_f32_e32 v102, v102
	v_rcp_f32_e32 v103, v103
	s_nop 0
	v_mul_f32_e32 v68, v68, v100
	v_mul_f32_e32 v69, v69, v101
	v_mul_f32_e32 v70, v70, v102
	v_mul_f32_e32 v71, v71, v103
	v_mul_f32_e32 v68, v76, v68
	v_mul_f32_e32 v69, v77, v69
	v_mul_f32_e32 v70, v78, v70
	v_mul_f32_e32 v71, v79, v71
	v_bfe_u32 v100, v68, 16, 1
	v_bfe_u32 v101, v69, 16, 1
	v_bfe_u32 v102, v70, 16, 1
	v_bfe_u32 v103, v71, 16, 1
	v_add3_u32 v68, v68, v100, s33
	v_add3_u32 v69, v69, v101, s33
	v_add3_u32 v70, v70, v102, s33
	v_add3_u32 v71, v71, v103, s33
	global_store_short_d16_hi v104, v68, s[4:5]
	global_store_short_d16_hi v105, v69, s[4:5]
	global_store_short_d16_hi v106, v70, s[4:5]
	global_store_short_d16_hi v107, v71, s[4:5]
	v_mul_f32_e32 v100, 0xbfb8aa3b, v80
	v_mul_f32_e32 v101, 0xbfb8aa3b, v81
	v_mul_f32_e32 v102, 0xbfb8aa3b, v82
	v_mul_f32_e32 v103, 0xbfb8aa3b, v83
	v_exp_f32_e32 v100, v100
	v_exp_f32_e32 v101, v101
	v_exp_f32_e32 v102, v102
	v_exp_f32_e32 v103, v103
	v_add_u32_e32 v104, 0x6e000, v98
	v_add_u32_e32 v105, 0x6f600, v98
	v_add_u32_e32 v106, 0x70c00, v98
	v_add_u32_e32 v107, 0x72200, v98
	v_add_f32_e32 v100, 1.0, v100
	v_add_f32_e32 v101, 1.0, v101
	v_add_f32_e32 v102, 1.0, v102
	v_add_f32_e32 v103, 1.0, v103
	v_rcp_f32_e32 v100, v100
	v_rcp_f32_e32 v101, v101
	v_rcp_f32_e32 v102, v102
	v_rcp_f32_e32 v103, v103
	s_nop 0
	v_mul_f32_e32 v80, v80, v100
	v_mul_f32_e32 v81, v81, v101
	v_mul_f32_e32 v82, v82, v102
	v_mul_f32_e32 v83, v83, v103
	v_mul_f32_e32 v80, v88, v80
	v_mul_f32_e32 v81, v89, v81
	v_mul_f32_e32 v82, v90, v82
	v_mul_f32_e32 v83, v91, v83
	v_bfe_u32 v100, v80, 16, 1
	v_bfe_u32 v101, v81, 16, 1
	v_bfe_u32 v102, v82, 16, 1
	v_bfe_u32 v103, v83, 16, 1
	v_add3_u32 v80, v80, v100, s33
	v_add3_u32 v81, v81, v101, s33
	v_add3_u32 v82, v82, v102, s33
	v_add3_u32 v83, v83, v103, s33
	global_store_short_d16_hi v104, v80, s[4:5]
	global_store_short_d16_hi v105, v81, s[4:5]
	global_store_short_d16_hi v106, v82, s[4:5]
	global_store_short_d16_hi v107, v83, s[4:5]
	v_mul_f32_e32 v100, 0xbfb8aa3b, v84
	v_mul_f32_e32 v101, 0xbfb8aa3b, v85
	v_mul_f32_e32 v102, 0xbfb8aa3b, v86
	v_mul_f32_e32 v103, 0xbfb8aa3b, v87
	v_exp_f32_e32 v100, v100
	v_exp_f32_e32 v101, v101
	v_exp_f32_e32 v102, v102
	v_exp_f32_e32 v103, v103
	v_add_u32_e32 v104, 0x6e020, v98
	v_add_u32_e32 v105, 0x6f620, v98
	v_add_u32_e32 v106, 0x70c20, v98
	v_add_u32_e32 v107, 0x72220, v98
	v_add_f32_e32 v100, 1.0, v100
	v_add_f32_e32 v101, 1.0, v101
	v_add_f32_e32 v102, 1.0, v102
	v_add_f32_e32 v103, 1.0, v103
	v_rcp_f32_e32 v100, v100
	v_rcp_f32_e32 v101, v101
	v_rcp_f32_e32 v102, v102
	v_rcp_f32_e32 v103, v103
	s_nop 0
	v_mul_f32_e32 v84, v84, v100
	v_mul_f32_e32 v85, v85, v101
	v_mul_f32_e32 v86, v86, v102
	v_mul_f32_e32 v87, v87, v103
	v_mul_f32_e32 v84, v92, v84
	v_mul_f32_e32 v85, v93, v85
	v_mul_f32_e32 v86, v94, v86
	v_mul_f32_e32 v87, v95, v87
	v_bfe_u32 v100, v84, 16, 1
	v_bfe_u32 v101, v85, 16, 1
	v_bfe_u32 v102, v86, 16, 1
	v_bfe_u32 v103, v87, 16, 1
	v_add3_u32 v84, v84, v100, s33
	v_add3_u32 v85, v85, v101, s33
	v_add3_u32 v86, v86, v102, s33
	v_add3_u32 v87, v87, v103, s33
	global_store_short_d16_hi v104, v84, s[4:5]
	global_store_short_d16_hi v105, v85, s[4:5]
	global_store_short_d16_hi v106, v86, s[4:5]
	global_store_short_d16_hi v107, v87, s[4:5]
	s_add_i32 s16, s16, s76
	s_cmpk_gt_i32 s16, 0x57f
	s_cbranch_scc1 .LBB0_1340
.LBB0_1336:
	s_ashr_i32 s14, s16, 31
	v_mov_b32_e32 v129, v127
	s_lshr_b32 s14, s14, 27
	s_add_i32 s14, s16, s14
	v_ashrrev_i32_e32 v20, 6, v129
	v_bfe_u32 v24, v129, 3, 3
	v_lshlrev_b32_e32 v25, 3, v20
	s_ashr_i32 s18, s14, 5
	s_and_b32 s14, s14, 0x3ffffe0
	v_or_b32_e32 v12, v25, v24
	s_sub_i32 s17, s16, s14
	v_lshrrev_b32_e32 v26, 1, v12
	s_mulk_i32 s17, 0xc0
	v_lshrrev_b32_e32 v0, 31, v129
	v_xor_b32_e32 v2, v26, v129
	v_add_u32_e32 v21, v20, v0
	v_and_b32_e32 v23, 63, v129
	v_add_u32_e32 v0, s17, v12
	v_lshlrev_b32_e32 v2, 4, v2
	v_add_u32_e32 v14, 32, v12
	v_ashrrev_i32_e32 v1, 31, v0
	v_and_b32_e32 v124, 0x70, v2
	v_add_u32_e32 v2, s17, v14
	v_add_u32_e32 v16, 64, v12
	s_add_i32 s15, s17, 0x80
	v_lshlrev_b32_e32 v23, 4, v23
	v_lshlrev_b64 v[0:1], 11, v[0:1]
	v_ashrrev_i32_e32 v3, 31, v2
	v_add_u32_e32 v4, s17, v16
	v_add_u32_e32 v18, 0x60, v12
	v_add_u32_e32 v8, s15, v12
	s_add_i32 s15, s17, 0xa0
	v_lshl_or_b32 v142, v20, 10, v23
	v_lshl_add_u64 v[0:1], s[6:7], 0, v[0:1]
	v_lshlrev_b64 v[2:3], 11, v[2:3]
	v_ashrrev_i32_e32 v5, 31, v4
	v_add_u32_e32 v6, s17, v18
	v_add_u32_e32 v10, s15, v12
	v_readfirstlane_b32 s15, v142
	v_add_u32_e32 v144, 0x1000, v142
	v_lshl_add_u64 v[0:1], v[0:1], 0, v[124:125]
	v_lshl_add_u64 v[2:3], s[6:7], 0, v[2:3]
	v_lshlrev_b64 v[4:5], 11, v[4:5]
	v_ashrrev_i32_e32 v7, 31, v6
	s_mov_b32 m0, s15
	v_readfirstlane_b32 s15, v144
	v_add_u32_e32 v145, 0x2000, v142
	s_lshl_b32 s14, s18, 7
	v_lshl_add_u64 v[2:3], v[2:3], 0, v[124:125]
	v_lshl_add_u64 v[4:5], s[6:7], 0, v[4:5]
	v_lshlrev_b64 v[6:7], 11, v[6:7]
	v_ashrrev_i32_e32 v9, 31, v8
	global_load_lds_dwordx4 v[0:1], off
	s_mov_b32 m0, s15
	v_readfirstlane_b32 s15, v145
	v_add_u32_e32 v146, 0x3000, v142
	v_lshl_add_u64 v[4:5], v[4:5], 0, v[124:125]
	v_lshl_add_u64 v[6:7], s[6:7], 0, v[6:7]
	v_lshlrev_b64 v[8:9], 11, v[8:9]
	v_ashrrev_i32_e32 v11, 31, v10
	v_add_u32_e32 v12, s14, v12
	global_load_lds_dwordx4 v[2:3], off
	s_mov_b32 m0, s15
	v_readfirstlane_b32 s15, v146
	v_add_u32_e32 v147, 0x4000, v142
	v_lshl_add_u64 v[6:7], v[6:7], 0, v[124:125]
	v_lshl_add_u64 v[8:9], s[6:7], 0, v[8:9]
	v_lshlrev_b64 v[10:11], 11, v[10:11]
	v_ashrrev_i32_e32 v13, 31, v12
	v_add_u32_e32 v14, s14, v14
	global_load_lds_dwordx4 v[4:5], off
	s_mov_b32 m0, s15
	v_readfirstlane_b32 s15, v147
	v_add_u32_e32 v148, 0x5000, v142
	v_lshl_add_u64 v[8:9], v[8:9], 0, v[124:125]
	v_lshl_add_u64 v[10:11], s[6:7], 0, v[10:11]
	v_lshlrev_b64 v[12:13], 11, v[12:13]
	v_ashrrev_i32_e32 v15, 31, v14
	v_add_u32_e32 v16, s14, v16
	v_add_u32_e32 v143, 0xc000, v142
	global_load_lds_dwordx4 v[6:7], off
	s_mov_b32 m0, s15
	v_readfirstlane_b32 s15, v148
	v_lshl_add_u64 v[10:11], v[10:11], 0, v[124:125]
	v_lshl_add_u64 v[12:13], s[10:11], 0, v[12:13]
	v_lshlrev_b64 v[14:15], 11, v[14:15]
	v_ashrrev_i32_e32 v17, 31, v16
	v_add_u32_e32 v18, s14, v18
	global_load_lds_dwordx4 v[8:9], off
	s_mov_b32 m0, s15
	v_readfirstlane_b32 s15, v143
	v_add_u32_e32 v150, 0xd000, v142
	v_lshl_add_u64 v[12:13], v[12:13], 0, v[124:125]
	v_lshl_add_u64 v[14:15], s[10:11], 0, v[14:15]
	v_lshlrev_b64 v[16:17], 11, v[16:17]
	v_ashrrev_i32_e32 v19, 31, v18
	global_load_lds_dwordx4 v[10:11], off
	s_mov_b32 m0, s15
	v_readfirstlane_b32 s15, v150
	v_add_u32_e32 v153, 0xe000, v142
	v_lshl_add_u64 v[14:15], v[14:15], 0, v[124:125]
	v_lshl_add_u64 v[16:17], s[10:11], 0, v[16:17]
	v_lshlrev_b64 v[18:19], 11, v[18:19]
	global_load_lds_dwordx4 v[12:13], off
	s_mov_b32 m0, s15
	v_readfirstlane_b32 s15, v153
	v_add_u32_e32 v154, 0xf000, v142
	v_lshl_add_u64 v[16:17], v[16:17], 0, v[124:125]
	v_lshl_add_u64 v[18:19], s[10:11], 0, v[18:19]
	global_load_lds_dwordx4 v[14:15], off
	s_mov_b32 m0, s15
	v_readfirstlane_b32 s15, v154
	v_lshl_add_u64 v[18:19], v[18:19], 0, v[124:125]
	global_load_lds_dwordx4 v[16:17], off
	s_mov_b32 m0, s15
	v_lshrrev_b32_e32 v22, 1, v21
	global_load_lds_dwordx4 v[18:19], off
	v_and_b32_e32 v149, 31, v129
	v_mul_lo_u32 v152, v22, s80
	v_and_b32_e32 v0, -2, v21
	v_or_b32_e32 v1, v152, v149
	v_sub_u32_e32 v151, v20, v0
	v_lshlrev_b32_e32 v155, 7, v1
	v_lshlrev_b32_e32 v1, 7, v149
	v_lshrrev_b32_e32 v23, 1, v129
	v_lshl_or_b32 v182, v151, 13, v1
	v_bfe_u32 v1, v129, 5, 1
	v_bfe_u32 v0, v129, 1, 3
	v_bitop3_b32 v2, v1, v23, 7 bitop3:0x78
	v_lshlrev_b32_e32 v184, 4, v2
	v_bitop3_b32 v2, v1, v0, 2 bitop3:0x36
	v_lshlrev_b32_e32 v185, 4, v2
	v_bitop3_b32 v2, v1, v0, 4 bitop3:0x36
	v_bitop3_b32 v0, v1, v0, 6 bitop3:0x36
	v_lshlrev_b32_e32 v187, 4, v0
	v_bitop3_b32 v0, v26, 7, v129 bitop3:0x48
	s_mul_i32 s15, s16, 0xc0
	v_lshlrev_b32_e32 v124, 4, v0
	v_or_b32_e32 v0, s15, v24
	v_add_u32_e32 v0, v0, v25
	s_mul_i32 s19, s18, 0x1800
	v_subrev_u32_e32 v0, s19, v0
	v_ashrrev_i32_e32 v1, 31, v0
	v_or_b32_e32 v4, 32, v24
	v_lshlrev_b32_e32 v186, 4, v2
	v_lshlrev_b64 v[2:3], 11, v[0:1]
	v_or_b32_e32 v1, s15, v4
	v_add_u32_e32 v1, v1, v25
	v_lshl_add_u64 v[96:97], s[6:7], 0, v[2:3]
	v_subrev_u32_e32 v2, s19, v1
	v_ashrrev_i32_e32 v3, 31, v2
	v_or_b32_e32 v5, 64, v24
	v_lshlrev_b64 v[2:3], 11, v[2:3]
	v_add3_u32 v1, v5, s15, v25
	v_lshl_add_u64 v[98:99], s[6:7], 0, v[2:3]
	v_subrev_u32_e32 v2, s19, v1
	v_ashrrev_i32_e32 v3, 31, v2
	v_or_b32_e32 v6, 0x60, v24
	v_lshlrev_b64 v[2:3], 11, v[2:3]
	v_add3_u32 v1, v6, s15, v25
	v_lshl_add_u64 v[100:101], s[6:7], 0, v[2:3]
	v_subrev_u32_e32 v2, s19, v1
	v_ashrrev_i32_e32 v3, 31, v2
	v_lshlrev_b64 v[2:3], 11, v[2:3]
	v_lshl_add_u64 v[102:103], s[6:7], 0, v[2:3]
	v_add_u32_e32 v2, 0x80, v0
	v_add_u32_e32 v0, 0xa0, v0
	v_ashrrev_i32_e32 v1, 31, v0
	v_lshlrev_b64 v[0:1], 11, v[0:1]
	v_lshl_add_u64 v[106:107], s[6:7], 0, v[0:1]
	v_or_b32_e32 v0, s14, v24
	v_add_u32_e32 v0, v0, v25
	v_ashrrev_i32_e32 v1, 31, v0
	v_lshlrev_b64 v[0:1], 11, v[0:1]
	v_lshl_add_u64 v[108:109], s[12:13], 0, v[0:1]
	v_or_b32_e32 v0, s14, v4
	v_add_u32_e32 v0, v0, v25
	v_ashrrev_i32_e32 v1, 31, v0
	v_lshlrev_b64 v[0:1], 11, v[0:1]
	v_lshl_add_u64 v[110:111], s[12:13], 0, v[0:1]
	v_or_b32_e32 v0, s14, v5
	v_add_u32_e32 v0, v0, v25
	v_ashrrev_i32_e32 v1, 31, v0
	v_lshlrev_b64 v[0:1], 11, v[0:1]
	v_lshl_add_u64 v[112:113], s[12:13], 0, v[0:1]
	v_or_b32_e32 v0, s14, v6
	v_add_u32_e32 v0, v0, v25
	s_waitcnt vmcnt(0)
	v_ashrrev_i32_e32 v3, 31, v2
	v_ashrrev_i32_e32 v1, 31, v0
	v_lshlrev_b64 v[2:3], 11, v[2:3]
	v_lshlrev_b64 v[0:1], 11, v[0:1]
	v_mov_b32_e32 v64, 0
	v_add_u32_e32 v183, 0x10000, v182
	v_lshl_add_u64 v[104:105], s[6:7], 0, v[2:3]
	v_lshl_add_u64 v[114:115], s[12:13], 0, v[0:1]
	s_mov_b32 s19, 0
	v_mov_b32_e32 v65, v64
	v_mov_b32_e32 v66, v64
	v_mov_b32_e32 v67, v64
	v_mov_b32_e32 v68, v64
	v_mov_b32_e32 v69, v64
	v_mov_b32_e32 v70, v64
	v_mov_b32_e32 v71, v64
	v_mov_b32_e32 v72, v64
	v_mov_b32_e32 v73, v64
	v_mov_b32_e32 v74, v64
	v_mov_b32_e32 v75, v64
	v_mov_b32_e32 v76, v64
	v_mov_b32_e32 v77, v64
	v_mov_b32_e32 v78, v64
	v_mov_b32_e32 v79, v64
	v_mov_b32_e32 v80, v64
	v_mov_b32_e32 v81, v64
	v_mov_b32_e32 v82, v64
	v_mov_b32_e32 v83, v64
	v_mov_b32_e32 v84, v64
	v_mov_b32_e32 v85, v64
	v_mov_b32_e32 v86, v64
	v_mov_b32_e32 v87, v64
	v_mov_b32_e32 v88, v64
	v_mov_b32_e32 v89, v64
	v_mov_b32_e32 v90, v64
	v_mov_b32_e32 v91, v64
	v_mov_b32_e32 v92, v64
	v_mov_b32_e32 v93, v64
	v_mov_b32_e32 v94, v64
	v_mov_b32_e32 v95, v64
	v_mov_b32_e32 v32, v64
	v_mov_b32_e32 v33, v64
	v_mov_b32_e32 v34, v64
	v_mov_b32_e32 v35, v64
	v_mov_b32_e32 v36, v64
	v_mov_b32_e32 v37, v64
	v_mov_b32_e32 v38, v64
	v_mov_b32_e32 v39, v64
	v_mov_b32_e32 v40, v64
	v_mov_b32_e32 v41, v64
	v_mov_b32_e32 v42, v64
	v_mov_b32_e32 v43, v64
	v_mov_b32_e32 v44, v64
	v_mov_b32_e32 v45, v64
	v_mov_b32_e32 v46, v64
	v_mov_b32_e32 v47, v64
	v_mov_b32_e32 v48, v64
	v_mov_b32_e32 v49, v64
	v_mov_b32_e32 v50, v64
	v_mov_b32_e32 v51, v64
	v_mov_b32_e32 v52, v64
	v_mov_b32_e32 v53, v64
	v_mov_b32_e32 v54, v64
	v_mov_b32_e32 v55, v64
	v_mov_b32_e32 v56, v64
	v_mov_b32_e32 v57, v64
	v_mov_b32_e32 v58, v64
	v_mov_b32_e32 v59, v64
	v_mov_b32_e32 v60, v64
	v_mov_b32_e32 v61, v64
	v_mov_b32_e32 v62, v64
	v_mov_b32_e32 v63, v64
	v_mov_b32_e32 v0, v64
	v_mov_b32_e32 v1, v64
	v_mov_b32_e32 v2, v64
	v_mov_b32_e32 v3, v64
	v_mov_b32_e32 v4, v64
	v_mov_b32_e32 v5, v64
	v_mov_b32_e32 v6, v64
	v_mov_b32_e32 v7, v64
	v_mov_b32_e32 v8, v64
	v_mov_b32_e32 v9, v64
	v_mov_b32_e32 v10, v64
	v_mov_b32_e32 v11, v64
	v_mov_b32_e32 v12, v64
	v_mov_b32_e32 v13, v64
	v_mov_b32_e32 v14, v64
	v_mov_b32_e32 v15, v64
	v_mov_b32_e32 v16, v64
	v_mov_b32_e32 v17, v64
	v_mov_b32_e32 v18, v64
	v_mov_b32_e32 v19, v64
	v_mov_b32_e32 v20, v64
	v_mov_b32_e32 v21, v64
	v_mov_b32_e32 v22, v64
	v_mov_b32_e32 v23, v64
	v_mov_b32_e32 v24, v64
	v_mov_b32_e32 v25, v64
	v_mov_b32_e32 v26, v64
	v_mov_b32_e32 v27, v64
	v_mov_b32_e32 v28, v64
	v_mov_b32_e32 v29, v64
	v_mov_b32_e32 v30, v64
	v_mov_b32_e32 v31, v64
	s_waitcnt vmcnt(0) lgkmcnt(0)
	s_barrier
	v_readfirstlane_b32 s101, v142
	s_sub_u32 vcc_lo, s10, s12
	s_subb_u32 vcc_hi, s11, s13
	v_mov_b32_e32 v130, v124
	v_mov_b32_e32 v131, 0
	v_lshl_add_u64 v[108:109], v[108:109], 0, vcc
	v_lshl_add_u64 v[110:111], v[110:111], 0, vcc
	v_lshl_add_u64 v[112:113], v[112:113], 0, vcc
	v_lshl_add_u64 v[114:115], v[114:115], 0, vcc
	v_lshl_add_u64 v[96:97], v[96:97], 0, v[130:131]
	v_lshl_add_u64 v[98:99], v[98:99], 0, v[130:131]
	v_lshl_add_u64 v[100:101], v[100:101], 0, v[130:131]
	v_lshl_add_u64 v[102:103], v[102:103], 0, v[130:131]
	v_lshl_add_u64 v[104:105], v[104:105], 0, v[130:131]
	v_lshl_add_u64 v[106:107], v[106:107], 0, v[130:131]
	v_lshl_add_u64 v[108:109], v[108:109], 0, v[130:131]
	v_lshl_add_u64 v[110:111], v[110:111], 0, v[130:131]
	v_lshl_add_u64 v[112:113], v[112:113], 0, v[130:131]
	v_lshl_add_u64 v[114:115], v[114:115], 0, v[130:131]
	v_and_b32_e32 v130, 15, v129
	v_bfe_u32 v131, v129, 4, 2
	v_bfe_u32 v116, v129, 1, 3
	v_xor_b32_e32 v117, v131, v116
	v_lshlrev_b32_e32 v117, 4, v117
	v_xor_b32_e32 v118, 64, v117
	v_lshrrev_b32_e32 v119, 7, v129
	v_mul_u32_u24_e32 v119, 0x60, v119
	v_add_u32_e32 v119, v119, v130
	v_lshlrev_b32_e32 v119, 7, v119
	v_bfe_u32 v120, v129, 6, 1
	v_lshl_add_u32 v120, v120, 6, v130
	v_lshlrev_b32_e32 v120, 7, v120
	v_add_u32_e32 v120, 0x8000, v120
	v_add_u32_e32 v150, v119, v117
	v_add_u32_e32 v153, v119, v118
	v_add_u32_e32 v154, v120, v117
	v_add_u32_e32 v155, v120, v118
	v_lshl_add_u64 v[96:97], v[96:97], 0, s[2:3]
	v_lshl_add_u64 v[98:99], v[98:99], 0, s[2:3]
	v_lshl_add_u64 v[100:101], v[100:101], 0, s[2:3]
	v_lshl_add_u64 v[102:103], v[102:103], 0, s[2:3]
	v_lshl_add_u64 v[104:105], v[104:105], 0, s[2:3]
	v_lshl_add_u64 v[106:107], v[106:107], 0, s[2:3]
	v_lshl_add_u64 v[108:109], v[108:109], 0, s[2:3]
	v_lshl_add_u64 v[110:111], v[110:111], 0, s[2:3]
	v_lshl_add_u64 v[112:113], v[112:113], 0, s[2:3]
	v_lshl_add_u64 v[114:115], v[114:115], 0, s[2:3]
	ds_read_b128 v[182:185], v150 offset:0
	ds_read_b128 v[206:209], v154 offset:16384
	ds_read_b128 v[210:213], v154 offset:18432
	ds_read_b128 v[214:217], v154 offset:20480
	ds_read_b128 v[218:221], v154 offset:22528
	ds_read_b128 v[186:189], v150 offset:2048
	ds_read_b128 v[190:193], v150 offset:4096
	ds_read_b128 v[194:197], v150 offset:6144
	ds_read_b128 v[198:201], v150 offset:8192
	ds_read_b128 v[202:205], v150 offset:10240
	s_add_u32 m0, s101, 0x6000
	s_nop 0
	global_load_lds_dwordx4 v[96:97], off
	v_lshl_add_u64 v[96:97], v[96:97], 0, s[2:3]
	s_add_u32 m0, s101, 0x7000
	s_nop 0
	global_load_lds_dwordx4 v[98:99], off
	v_lshl_add_u64 v[98:99], v[98:99], 0, s[2:3]
	s_add_u32 m0, s101, 0x8000
	s_nop 0
	global_load_lds_dwordx4 v[100:101], off
	v_lshl_add_u64 v[100:101], v[100:101], 0, s[2:3]
	s_add_u32 m0, s101, 0x9000
	s_nop 0
	global_load_lds_dwordx4 v[102:103], off
	v_lshl_add_u64 v[102:103], v[102:103], 0, s[2:3]
	s_add_u32 m0, s101, 0xa000
	s_nop 0
	global_load_lds_dwordx4 v[104:105], off
	v_lshl_add_u64 v[104:105], v[104:105], 0, s[2:3]
	s_mov_b32 s100, 7
